# all individually validated micro-edits combined on v20: shallow MLA LDS prefetch + store/prefetch segment at step tail, peeled GEMM K-loop tails, DPP butterfly steps (SSQ and LayerNorm reductions), LN
# speedup vs baseline: 1.0088x; 1.0080x over previous
.LBB0_1558:
	s_add_i32 s50, s46, -1
	s_add_i32 s47, s46, -4
	s_cmp_ge_i32 s47, s43
	s_cbranch_scc1 .LBB0_1562
	ds_read_b128 v[4:7], v225
	ds_read_b128 v[8:11], v225 offset:12800
	ds_read_b128 v[12:15], v225 offset:32
	s_waitcnt lgkmcnt(2)
	v_mfma_f32_32x32x16_bf16 v[96:111], v[4:7], v[156:159], 0
	ds_read_b128 v[228:231], v225 offset:12832
	s_waitcnt lgkmcnt(2)
	v_mfma_f32_32x32x16_bf16 v[80:95], v[8:11], v[156:159], 0
	ds_read_b128 v[4:7], v225 offset:64
	s_waitcnt lgkmcnt(2)
	v_mfma_f32_32x32x16_bf16 v[96:111], v[12:15], v[152:155], v[96:111]
	ds_read_b128 v[8:11], v225 offset:12864
	s_waitcnt lgkmcnt(2)
	v_mfma_f32_32x32x16_bf16 v[80:95], v[228:231], v[152:155], v[80:95]
	ds_read_b128 v[12:15], v225 offset:96
	s_waitcnt lgkmcnt(2)
	v_mfma_f32_32x32x16_bf16 v[96:111], v[4:7], v[148:151], v[96:111]
	ds_read_b128 v[228:231], v225 offset:12896
	s_waitcnt lgkmcnt(2)
	v_mfma_f32_32x32x16_bf16 v[80:95], v[8:11], v[148:151], v[80:95]
	ds_read_b128 v[4:7], v225 offset:128
	s_waitcnt lgkmcnt(2)
	v_mfma_f32_32x32x16_bf16 v[96:111], v[12:15], v[144:147], v[96:111]
	ds_read_b128 v[8:11], v225 offset:12928
	s_waitcnt lgkmcnt(2)
	v_mfma_f32_32x32x16_bf16 v[80:95], v[228:231], v[144:147], v[80:95]
	ds_read_b128 v[12:15], v225 offset:160
	s_waitcnt lgkmcnt(2)
	v_mfma_f32_32x32x16_bf16 v[96:111], v[4:7], v[140:143], v[96:111]
	ds_read_b128 v[228:231], v225 offset:12960
	s_waitcnt lgkmcnt(2)
	v_mfma_f32_32x32x16_bf16 v[80:95], v[8:11], v[140:143], v[80:95]
	ds_read_b128 v[4:7], v225 offset:192
	s_waitcnt lgkmcnt(2)
	v_mfma_f32_32x32x16_bf16 v[96:111], v[12:15], v[136:139], v[96:111]
	ds_read_b128 v[8:11], v225 offset:12992
	s_waitcnt lgkmcnt(2)
	v_mfma_f32_32x32x16_bf16 v[80:95], v[228:231], v[136:139], v[80:95]
	ds_read_b128 v[12:15], v225 offset:224
	s_waitcnt lgkmcnt(2)
	v_mfma_f32_32x32x16_bf16 v[96:111], v[4:7], v[132:135], v[96:111]
	ds_read_b128 v[228:231], v225 offset:13024
	s_waitcnt lgkmcnt(2)
	v_mfma_f32_32x32x16_bf16 v[80:95], v[8:11], v[132:135], v[80:95]
	ds_read_b128 v[4:7], v225 offset:256
	s_waitcnt lgkmcnt(2)
	v_mfma_f32_32x32x16_bf16 v[96:111], v[12:15], v[128:131], v[96:111]
	ds_read_b128 v[8:11], v225 offset:13056
	s_waitcnt lgkmcnt(2)
	v_mfma_f32_32x32x16_bf16 v[80:95], v[228:231], v[128:131], v[80:95]
	ds_read_b128 v[12:15], v225 offset:288
	s_waitcnt lgkmcnt(2)
	v_mfma_f32_32x32x16_bf16 v[96:111], v[4:7], v[124:127], v[96:111]
	ds_read_b128 v[228:231], v225 offset:13088
	s_waitcnt lgkmcnt(2)
	v_mfma_f32_32x32x16_bf16 v[80:95], v[8:11], v[124:127], v[80:95]
	ds_read_b128 v[4:7], v225 offset:320
	s_waitcnt lgkmcnt(2)
	v_mfma_f32_32x32x16_bf16 v[96:111], v[12:15], v[120:123], v[96:111]
	ds_read_b128 v[8:11], v225 offset:13120
	s_waitcnt lgkmcnt(2)
	v_mfma_f32_32x32x16_bf16 v[80:95], v[228:231], v[120:123], v[80:95]
	ds_read_b128 v[12:15], v225 offset:352
	s_waitcnt lgkmcnt(2)
	v_mfma_f32_32x32x16_bf16 v[96:111], v[4:7], v[116:119], v[96:111]
	ds_read_b128 v[228:231], v225 offset:13152
	s_waitcnt lgkmcnt(2)
	v_mfma_f32_32x32x16_bf16 v[80:95], v[8:11], v[116:119], v[80:95]
	s_waitcnt lgkmcnt(1)
	v_mfma_f32_32x32x16_bf16 v[96:111], v[12:15], v[112:115], v[96:111]
	s_waitcnt lgkmcnt(0)
	v_mfma_f32_32x32x16_bf16 v[80:95], v[228:231], v[112:115], v[80:95]
	v_and_b32_e32 v248, 64, v210
	v_xor_b32_e32 v249, 32, v210
	v_add_u32_e32 v248, 64, v248
	v_cmp_lt_i32_e32 vcc, v249, v248
	ds_read_b64 v[232:233], v223 offset:25600
	ds_read_b64 v[234:235], v223 offset:25616
	ds_read_b64 v[236:237], v223 offset:29952
	ds_read_b64 v[238:239], v223 offset:29968
	ds_read_b64 v[240:241], v223 offset:34304
	ds_read_b64 v[242:243], v223 offset:34320
	v_cndmask_b32_e32 v249, v210, v249, vcc
	v_lshlrev_b32_e32 v249, 2, v249
	s_nop 1
	v_max_f32_e32 v0, v96, v80
	v_max3_f32 v0, v0, v97, v81
	v_max3_f32 v0, v0, v98, v82
	v_max3_f32 v0, v0, v99, v83
	v_max3_f32 v0, v0, v100, v84
	v_max3_f32 v0, v0, v101, v85
	v_max3_f32 v0, v0, v102, v86
	v_max3_f32 v0, v0, v103, v87
	v_max3_f32 v0, v0, v104, v88
	v_max3_f32 v0, v0, v105, v89
	v_max3_f32 v0, v0, v106, v90
	v_max3_f32 v0, v0, v107, v91
	v_max3_f32 v0, v0, v108, v92
	v_max3_f32 v0, v0, v109, v93
	v_max3_f32 v0, v0, v110, v94
	v_max3_f32 v0, v0, v111, v95
	ds_bpermute_b32 v248, v249, v0
	s_waitcnt lgkmcnt(0)
	v_max_f32_e32 v0, v0, v248
	v_max_f32_e32 v248, v226, v226
	v_max_f32_e32 v0, v0, v0
	v_sub_f32_e32 v249, v0, v248
	v_cmp_lt_f32_e32 vcc, 0x41000000, v249
	s_cbranch_vccz .Lmla_keep_a
	v_max_f32_e32 v2, v248, v0
	v_sub_f32_e32 v0, v226, v2
	v_exp_f32_e32 v0, v0
	s_nop 0
	v_pk_mul_f32 v[78:79], v[78:79], v[0:1] op_sel_hi:[1,0]
	v_pk_mul_f32 v[76:77], v[76:77], v[0:1] op_sel_hi:[1,0]
	v_pk_mul_f32 v[74:75], v[74:75], v[0:1] op_sel_hi:[1,0]
	v_pk_mul_f32 v[72:73], v[72:73], v[0:1] op_sel_hi:[1,0]
	v_pk_mul_f32 v[70:71], v[70:71], v[0:1] op_sel_hi:[1,0]
	v_pk_mul_f32 v[68:69], v[68:69], v[0:1] op_sel_hi:[1,0]
	v_pk_mul_f32 v[66:67], v[66:67], v[0:1] op_sel_hi:[1,0]
	v_pk_mul_f32 v[64:65], v[64:65], v[0:1] op_sel_hi:[1,0]
	v_pk_mul_f32 v[62:63], v[62:63], v[0:1] op_sel_hi:[1,0]
	v_pk_mul_f32 v[60:61], v[60:61], v[0:1] op_sel_hi:[1,0]
	v_pk_mul_f32 v[58:59], v[58:59], v[0:1] op_sel_hi:[1,0]
	v_pk_mul_f32 v[56:57], v[56:57], v[0:1] op_sel_hi:[1,0]
	v_pk_mul_f32 v[54:55], v[54:55], v[0:1] op_sel_hi:[1,0]
	v_pk_mul_f32 v[52:53], v[52:53], v[0:1] op_sel_hi:[1,0]
	v_pk_mul_f32 v[50:51], v[50:51], v[0:1] op_sel_hi:[1,0]
	v_pk_mul_f32 v[48:49], v[48:49], v[0:1] op_sel_hi:[1,0]
	v_pk_mul_f32 v[46:47], v[46:47], v[0:1] op_sel_hi:[1,0]
	v_pk_mul_f32 v[44:45], v[44:45], v[0:1] op_sel_hi:[1,0]
	v_pk_mul_f32 v[42:43], v[42:43], v[0:1] op_sel_hi:[1,0]
	v_pk_mul_f32 v[40:41], v[40:41], v[0:1] op_sel_hi:[1,0]
	v_pk_mul_f32 v[38:39], v[38:39], v[0:1] op_sel_hi:[1,0]
	v_pk_mul_f32 v[36:37], v[36:37], v[0:1] op_sel_hi:[1,0]
	v_pk_mul_f32 v[34:35], v[34:35], v[0:1] op_sel_hi:[1,0]
	v_pk_mul_f32 v[32:33], v[32:33], v[0:1] op_sel_hi:[1,0]
	v_pk_mul_f32 v[30:31], v[30:31], v[0:1] op_sel_hi:[1,0]
	v_pk_mul_f32 v[28:29], v[28:29], v[0:1] op_sel_hi:[1,0]
	v_pk_mul_f32 v[26:27], v[26:27], v[0:1] op_sel_hi:[1,0]
	v_pk_mul_f32 v[24:25], v[24:25], v[0:1] op_sel_hi:[1,0]
	v_pk_mul_f32 v[22:23], v[22:23], v[0:1] op_sel_hi:[1,0]
	v_pk_mul_f32 v[20:21], v[20:21], v[0:1] op_sel_hi:[1,0]
	v_pk_mul_f32 v[18:19], v[18:19], v[0:1] op_sel_hi:[1,0]
	v_pk_mul_f32 v[16:17], v[16:17], v[0:1] op_sel_hi:[1,0]
	s_branch .Lmla_join_a
	.Lmla_keep_a:
	v_mov_b32_e32 v2, v248
	v_mov_b32_e32 v0, 1.0
	.Lmla_join_a:
	v_sub_f32_e32 v248, v96, v2
	v_exp_f32_e32 v96, v248
	v_sub_f32_e32 v249, v97, v2
	v_exp_f32_e32 v97, v249
	v_sub_f32_e32 v248, v98, v2
	v_exp_f32_e32 v98, v248
	v_sub_f32_e32 v249, v99, v2
	v_exp_f32_e32 v99, v249
	v_sub_f32_e32 v248, v100, v2
	v_exp_f32_e32 v100, v248
	v_sub_f32_e32 v249, v101, v2
	v_exp_f32_e32 v101, v249
	v_sub_f32_e32 v248, v102, v2
	v_exp_f32_e32 v102, v248
	v_sub_f32_e32 v249, v103, v2
	v_exp_f32_e32 v103, v249
	s_nop 0
	v_cvt_pk_bf16_f32 v8, v96, v97
	v_cvt_pk_bf16_f32 v9, v98, v99
	v_cvt_pk_bf16_f32 v10, v100, v101
	v_cvt_pk_bf16_f32 v11, v102, v103
	v_sub_f32_e32 v248, v104, v2
	v_exp_f32_e32 v104, v248
	v_mfma_f32_32x32x16_bf16 v[64:79], v[232:235], v[8:11], v[64:79]
	ds_read_b64 v[232:233], v223 offset:38656
	ds_read_b64 v[234:235], v223 offset:38672
	v_sub_f32_e32 v249, v105, v2
	v_exp_f32_e32 v105, v249
	v_mfma_f32_32x32x16_bf16 v[48:63], v[236:239], v[8:11], v[48:63]
	ds_read_b64 v[236:237], v223 offset:25632
	ds_read_b64 v[238:239], v223 offset:25648
	v_sub_f32_e32 v248, v106, v2
	v_exp_f32_e32 v106, v248
	v_sub_f32_e32 v249, v107, v2
	v_exp_f32_e32 v107, v249
	v_mfma_f32_32x32x16_bf16 v[32:47], v[240:243], v[8:11], v[32:47]
	ds_read_b64 v[240:241], v223 offset:29984
	ds_read_b64 v[242:243], v223 offset:30000
	v_sub_f32_e32 v248, v108, v2
	v_exp_f32_e32 v108, v248
	v_sub_f32_e32 v249, v109, v2
	v_exp_f32_e32 v109, v249
	s_waitcnt lgkmcnt(4)
	v_mfma_f32_32x32x16_bf16 v[16:31], v[232:235], v[8:11], v[16:31]
	ds_read_b64 v[232:233], v223 offset:34336
	ds_read_b64 v[234:235], v223 offset:34352
	v_sub_f32_e32 v248, v110, v2
	v_exp_f32_e32 v110, v248
	v_sub_f32_e32 v249, v111, v2
	v_exp_f32_e32 v111, v249
	s_nop 0
	v_cvt_pk_bf16_f32 v4, v104, v105
	v_cvt_pk_bf16_f32 v5, v106, v107
	v_cvt_pk_bf16_f32 v6, v108, v109
	v_cvt_pk_bf16_f32 v7, v110, v111
	s_nop 1
	s_waitcnt lgkmcnt(4)
	v_mfma_f32_32x32x16_bf16 v[64:79], v[236:239], v[4:7], v[64:79]
	ds_read_b64 v[236:237], v223 offset:38688
	ds_read_b64 v[238:239], v223 offset:38704
	v_sub_f32_e32 v248, v80, v2
	v_exp_f32_e32 v80, v248
	v_sub_f32_e32 v249, v81, v2
	v_exp_f32_e32 v81, v249
	s_waitcnt lgkmcnt(4)
	v_mfma_f32_32x32x16_bf16 v[48:63], v[240:243], v[4:7], v[48:63]
	ds_read_b64 v[240:241], v223 offset:25664
	ds_read_b64 v[242:243], v223 offset:25680
	v_sub_f32_e32 v248, v82, v2
	v_exp_f32_e32 v82, v248
	v_sub_f32_e32 v249, v83, v2
	v_exp_f32_e32 v83, v249
	s_waitcnt lgkmcnt(4)
	v_mfma_f32_32x32x16_bf16 v[32:47], v[232:235], v[4:7], v[32:47]
	ds_read_b64 v[232:233], v223 offset:30016
	ds_read_b64 v[234:235], v223 offset:30032
	v_sub_f32_e32 v248, v84, v2
	v_exp_f32_e32 v84, v248
	v_sub_f32_e32 v249, v85, v2
	v_exp_f32_e32 v85, v249
	s_waitcnt lgkmcnt(4)
	v_mfma_f32_32x32x16_bf16 v[16:31], v[236:239], v[4:7], v[16:31]
	ds_read_b64 v[236:237], v223 offset:34368
	ds_read_b64 v[238:239], v223 offset:34384
	v_sub_f32_e32 v248, v86, v2
	v_exp_f32_e32 v86, v248
	v_sub_f32_e32 v249, v87, v2
	v_exp_f32_e32 v87, v249
	s_nop 0
	v_cvt_pk_bf16_f32 v12, v80, v81
	v_cvt_pk_bf16_f32 v13, v82, v83
	v_cvt_pk_bf16_f32 v14, v84, v85
	v_cvt_pk_bf16_f32 v15, v86, v87
	s_nop 1
	s_waitcnt lgkmcnt(4)
	v_mfma_f32_32x32x16_bf16 v[64:79], v[240:243], v[12:15], v[64:79]
	ds_read_b64 v[240:241], v223 offset:38720
	ds_read_b64 v[242:243], v223 offset:38736
	v_sub_f32_e32 v248, v88, v2
	v_exp_f32_e32 v88, v248
	v_sub_f32_e32 v249, v89, v2
	v_exp_f32_e32 v89, v249
	s_waitcnt lgkmcnt(4)
	v_mfma_f32_32x32x16_bf16 v[48:63], v[232:235], v[12:15], v[48:63]
	ds_read_b64 v[232:233], v223 offset:25696
	ds_read_b64 v[234:235], v223 offset:25712
	v_sub_f32_e32 v248, v90, v2
	v_exp_f32_e32 v90, v248
	v_sub_f32_e32 v249, v91, v2
	v_exp_f32_e32 v91, v249
	s_waitcnt lgkmcnt(4)
	v_mfma_f32_32x32x16_bf16 v[32:47], v[236:239], v[12:15], v[32:47]
	ds_read_b64 v[236:237], v223 offset:30048
	ds_read_b64 v[238:239], v223 offset:30064
	v_sub_f32_e32 v248, v92, v2
	v_exp_f32_e32 v92, v248
	v_sub_f32_e32 v249, v93, v2
	v_exp_f32_e32 v93, v249
	s_waitcnt lgkmcnt(4)
	v_mfma_f32_32x32x16_bf16 v[16:31], v[240:243], v[12:15], v[16:31]
	ds_read_b64 v[240:241], v223 offset:34400
	ds_read_b64 v[242:243], v223 offset:34416
	v_sub_f32_e32 v248, v94, v2
	v_exp_f32_e32 v94, v248
	v_sub_f32_e32 v249, v95, v2
	v_exp_f32_e32 v95, v249
	s_nop 0
	v_cvt_pk_bf16_f32 v8, v88, v89
	v_cvt_pk_bf16_f32 v9, v90, v91
	v_cvt_pk_bf16_f32 v10, v92, v93
	v_cvt_pk_bf16_f32 v11, v94, v95
	s_nop 1
	s_waitcnt lgkmcnt(4)
	v_mfma_f32_32x32x16_bf16 v[64:79], v[232:235], v[8:11], v[64:79]
	ds_read_b64 v[232:233], v223 offset:38752
	ds_read_b64 v[234:235], v223 offset:38768
	v_add_f32_e32 v3, v80, v96
	v_add_f32_e32 v248, v81, v97
	v_add_f32_e32 v3, v248, v3
	v_add_f32_e32 v249, v82, v98
	v_add_f32_e32 v3, v249, v3
	v_add_f32_e32 v248, v83, v99
	v_add_f32_e32 v3, v248, v3
	v_add_f32_e32 v249, v84, v100
	s_waitcnt lgkmcnt(4)
	v_mfma_f32_32x32x16_bf16 v[48:63], v[236:239], v[8:11], v[48:63]
	v_add_f32_e32 v3, v249, v3
	v_add_f32_e32 v248, v85, v101
	v_add_f32_e32 v3, v248, v3
	v_add_f32_e32 v249, v86, v102
	v_add_f32_e32 v3, v249, v3
	v_add_f32_e32 v248, v87, v103
	v_add_f32_e32 v3, v248, v3
	v_add_f32_e32 v249, v88, v104
	s_waitcnt lgkmcnt(2)
	v_mfma_f32_32x32x16_bf16 v[32:47], v[240:243], v[8:11], v[32:47]
	v_add_f32_e32 v3, v249, v3
	v_add_f32_e32 v248, v89, v105
	v_add_f32_e32 v3, v248, v3
	v_add_f32_e32 v249, v90, v106
	v_add_f32_e32 v3, v249, v3
	v_add_f32_e32 v248, v91, v107
	v_add_f32_e32 v3, v248, v3
	v_add_f32_e32 v249, v92, v108
	s_waitcnt lgkmcnt(0)
	v_mfma_f32_32x32x16_bf16 v[16:31], v[232:235], v[8:11], v[16:31]
	v_add_f32_e32 v3, v249, v3
	v_add_f32_e32 v248, v93, v109
	v_add_f32_e32 v3, v248, v3
	v_add_f32_e32 v249, v94, v110
	v_add_f32_e32 v3, v249, v3
	v_add_f32_e32 v248, v95, v111
	v_add_f32_e32 v3, v248, v3
	v_fmac_f32_e32 v3, v221, v0
	v_mov_b32_e32 v221, v3
	s_branch .LBB0_1563

.LBB0_1563:
	v_min_u32_e32 v0, s50, v205
	v_mad_u64_u32 v[250:251], s[50:51], v0, s30, v[208:209]
	v_lshlrev_b32_e32 v0, 6, v0
	v_lshl_add_u64 v[4:5], v[0:1], 1, v[206:207]
	v_add_u32_e32 v0, 0xa800, v222
	s_waitcnt vmcnt(7)
	ds_write_b128 v216, v[164:167] offset:43008
	s_waitcnt vmcnt(8)
	ds_write_b128 v217, v[160:163] offset:43008
	s_waitcnt vmcnt(7)
	ds_write_b128 v218, v[168:171] offset:43008
	s_waitcnt vmcnt(3)
	ds_write2_b64 v0, v[180:181], v[182:183] offset1:1
	v_add_u32_e32 v0, 0xca00, v222
	s_waitcnt vmcnt(1)
	ds_write2_b64 v0, v[188:189], v[190:191] offset1:1
	v_add_co_u32_e32 v6, vcc, 0x2000, v250
	s_nop 1
	v_addc_co_u32_e32 v7, vcc, 0, v251, vcc
	v_add_co_u32_e32 v8, vcc, 0x4000, v250
	s_nop 1
	v_addc_co_u32_e32 v9, vcc, 0, v251, vcc
	global_load_dwordx4 v[160:163], v[6:7], off
	global_load_dwordx4 v[168:171], v[8:9], off
	global_load_dwordx4 v[164:167], v[250:251], off
	global_load_dwordx4 v[180:183], v[4:5], off
	v_add_co_u32_e32 v250, vcc, 0x310000, v4
	s_nop 1
	v_addc_co_u32_e32 v251, vcc, 0, v5, vcc
	global_load_dwordx4 v[188:191], v[250:251], off
	s_waitcnt lgkmcnt(0)
	s_barrier
	s_add_i32 s47, s47, 1
	s_cmp_ge_i32 s47, s43
	s_cbranch_scc1 .LBB0_1556
	ds_read_b128 v[4:7], v225 offset:43008
	ds_read_b128 v[8:11], v225 offset:55808
	ds_read_b128 v[12:15], v225 offset:43040
	s_waitcnt lgkmcnt(2)
	v_mfma_f32_32x32x16_bf16 v[96:111], v[4:7], v[156:159], 0
	ds_read_b128 v[228:231], v225 offset:55840
	s_waitcnt lgkmcnt(2)
	v_mfma_f32_32x32x16_bf16 v[80:95], v[8:11], v[156:159], 0
	ds_read_b128 v[4:7], v225 offset:43072
	s_waitcnt lgkmcnt(2)
	v_mfma_f32_32x32x16_bf16 v[96:111], v[12:15], v[152:155], v[96:111]
	ds_read_b128 v[8:11], v225 offset:55872
	s_waitcnt lgkmcnt(2)
	v_mfma_f32_32x32x16_bf16 v[80:95], v[228:231], v[152:155], v[80:95]
	ds_read_b128 v[12:15], v225 offset:43104
	s_waitcnt lgkmcnt(2)
	v_mfma_f32_32x32x16_bf16 v[96:111], v[4:7], v[148:151], v[96:111]
	ds_read_b128 v[228:231], v225 offset:55904
	s_waitcnt lgkmcnt(2)
	v_mfma_f32_32x32x16_bf16 v[80:95], v[8:11], v[148:151], v[80:95]
	ds_read_b128 v[4:7], v225 offset:43136
	s_waitcnt lgkmcnt(2)
	v_mfma_f32_32x32x16_bf16 v[96:111], v[12:15], v[144:147], v[96:111]
	ds_read_b128 v[8:11], v225 offset:55936
	s_waitcnt lgkmcnt(2)
	v_mfma_f32_32x32x16_bf16 v[80:95], v[228:231], v[144:147], v[80:95]
	ds_read_b128 v[12:15], v225 offset:43168
	s_waitcnt lgkmcnt(2)
	v_mfma_f32_32x32x16_bf16 v[96:111], v[4:7], v[140:143], v[96:111]
	ds_read_b128 v[228:231], v225 offset:55968
	s_waitcnt lgkmcnt(2)
	v_mfma_f32_32x32x16_bf16 v[80:95], v[8:11], v[140:143], v[80:95]
	ds_read_b128 v[4:7], v225 offset:43200
	s_waitcnt lgkmcnt(2)
	v_mfma_f32_32x32x16_bf16 v[96:111], v[12:15], v[136:139], v[96:111]
	ds_read_b128 v[8:11], v225 offset:56000
	s_waitcnt lgkmcnt(2)
	v_mfma_f32_32x32x16_bf16 v[80:95], v[228:231], v[136:139], v[80:95]
	ds_read_b128 v[12:15], v225 offset:43232
	s_waitcnt lgkmcnt(2)
	v_mfma_f32_32x32x16_bf16 v[96:111], v[4:7], v[132:135], v[96:111]
	ds_read_b128 v[228:231], v225 offset:56032
	s_waitcnt lgkmcnt(2)
	v_mfma_f32_32x32x16_bf16 v[80:95], v[8:11], v[132:135], v[80:95]
	ds_read_b128 v[4:7], v225 offset:43264
	s_waitcnt lgkmcnt(2)
	v_mfma_f32_32x32x16_bf16 v[96:111], v[12:15], v[128:131], v[96:111]
	ds_read_b128 v[8:11], v225 offset:56064
	s_waitcnt lgkmcnt(2)
	v_mfma_f32_32x32x16_bf16 v[80:95], v[228:231], v[128:131], v[80:95]
	ds_read_b128 v[12:15], v225 offset:43296
	s_waitcnt lgkmcnt(2)
	v_mfma_f32_32x32x16_bf16 v[96:111], v[4:7], v[124:127], v[96:111]
	ds_read_b128 v[228:231], v225 offset:56096
	s_waitcnt lgkmcnt(2)
	v_mfma_f32_32x32x16_bf16 v[80:95], v[8:11], v[124:127], v[80:95]
	ds_read_b128 v[4:7], v225 offset:43328
	s_waitcnt lgkmcnt(2)
	v_mfma_f32_32x32x16_bf16 v[96:111], v[12:15], v[120:123], v[96:111]
	ds_read_b128 v[8:11], v225 offset:56128
	s_waitcnt lgkmcnt(2)
	v_mfma_f32_32x32x16_bf16 v[80:95], v[228:231], v[120:123], v[80:95]
	ds_read_b128 v[12:15], v225 offset:43360
	s_waitcnt lgkmcnt(2)
	v_mfma_f32_32x32x16_bf16 v[96:111], v[4:7], v[116:119], v[96:111]
	ds_read_b128 v[228:231], v225 offset:56160
	s_waitcnt lgkmcnt(2)
	v_mfma_f32_32x32x16_bf16 v[80:95], v[8:11], v[116:119], v[80:95]
	s_waitcnt lgkmcnt(1)
	v_mfma_f32_32x32x16_bf16 v[96:111], v[12:15], v[112:115], v[96:111]
	s_waitcnt lgkmcnt(0)
	v_mfma_f32_32x32x16_bf16 v[80:95], v[228:231], v[112:115], v[80:95]
	v_and_b32_e32 v248, 64, v210
	v_xor_b32_e32 v249, 32, v210
	v_add_u32_e32 v248, 64, v248
	v_cmp_lt_i32_e32 vcc, v249, v248
	ds_read_b64 v[232:233], v224 offset:0
	ds_read_b64 v[234:235], v224 offset:16
	ds_read_b64 v[236:237], v224 offset:4352
	ds_read_b64 v[238:239], v224 offset:4368
	ds_read_b64 v[240:241], v224 offset:8704
	ds_read_b64 v[242:243], v224 offset:8720
	v_cndmask_b32_e32 v249, v210, v249, vcc
	v_lshlrev_b32_e32 v249, 2, v249
	s_nop 1
	v_max_f32_e32 v0, v96, v80
	v_max3_f32 v0, v0, v97, v81
	v_max3_f32 v0, v0, v98, v82
	v_max3_f32 v0, v0, v99, v83
	v_max3_f32 v0, v0, v100, v84
	v_max3_f32 v0, v0, v101, v85
	v_max3_f32 v0, v0, v102, v86
	v_max3_f32 v0, v0, v103, v87
	v_max3_f32 v0, v0, v104, v88
	v_max3_f32 v0, v0, v105, v89
	v_max3_f32 v0, v0, v106, v90
	v_max3_f32 v0, v0, v107, v91
	v_max3_f32 v0, v0, v108, v92
	v_max3_f32 v0, v0, v109, v93
	v_max3_f32 v0, v0, v110, v94
	v_max3_f32 v0, v0, v111, v95
	ds_bpermute_b32 v248, v249, v0
	s_waitcnt lgkmcnt(0)
	v_max_f32_e32 v0, v0, v248
	v_max_f32_e32 v248, v2, v2
	v_max_f32_e32 v0, v0, v0
	v_sub_f32_e32 v249, v0, v248
	v_cmp_lt_f32_e32 vcc, 0x41000000, v249
	s_cbranch_vccz .Lmla_keep_b
	v_max_f32_e32 v226, v248, v0
	v_sub_f32_e32 v0, v2, v226
	v_exp_f32_e32 v0, v0
	s_nop 0
	v_pk_mul_f32 v[78:79], v[78:79], v[0:1] op_sel_hi:[1,0]
	v_pk_mul_f32 v[76:77], v[76:77], v[0:1] op_sel_hi:[1,0]
	v_pk_mul_f32 v[74:75], v[74:75], v[0:1] op_sel_hi:[1,0]
	v_pk_mul_f32 v[72:73], v[72:73], v[0:1] op_sel_hi:[1,0]
	v_pk_mul_f32 v[70:71], v[70:71], v[0:1] op_sel_hi:[1,0]
	v_pk_mul_f32 v[68:69], v[68:69], v[0:1] op_sel_hi:[1,0]
	v_pk_mul_f32 v[66:67], v[66:67], v[0:1] op_sel_hi:[1,0]
	v_pk_mul_f32 v[64:65], v[64:65], v[0:1] op_sel_hi:[1,0]
	v_pk_mul_f32 v[62:63], v[62:63], v[0:1] op_sel_hi:[1,0]
	v_pk_mul_f32 v[60:61], v[60:61], v[0:1] op_sel_hi:[1,0]
	v_pk_mul_f32 v[58:59], v[58:59], v[0:1] op_sel_hi:[1,0]
	v_pk_mul_f32 v[56:57], v[56:57], v[0:1] op_sel_hi:[1,0]
	v_pk_mul_f32 v[54:55], v[54:55], v[0:1] op_sel_hi:[1,0]
	v_pk_mul_f32 v[52:53], v[52:53], v[0:1] op_sel_hi:[1,0]
	v_pk_mul_f32 v[50:51], v[50:51], v[0:1] op_sel_hi:[1,0]
	v_pk_mul_f32 v[48:49], v[48:49], v[0:1] op_sel_hi:[1,0]
	v_pk_mul_f32 v[46:47], v[46:47], v[0:1] op_sel_hi:[1,0]
	v_pk_mul_f32 v[44:45], v[44:45], v[0:1] op_sel_hi:[1,0]
	v_pk_mul_f32 v[42:43], v[42:43], v[0:1] op_sel_hi:[1,0]
	v_pk_mul_f32 v[40:41], v[40:41], v[0:1] op_sel_hi:[1,0]
	v_pk_mul_f32 v[38:39], v[38:39], v[0:1] op_sel_hi:[1,0]
	v_pk_mul_f32 v[36:37], v[36:37], v[0:1] op_sel_hi:[1,0]
	v_pk_mul_f32 v[34:35], v[34:35], v[0:1] op_sel_hi:[1,0]
	v_pk_mul_f32 v[32:33], v[32:33], v[0:1] op_sel_hi:[1,0]
	v_pk_mul_f32 v[30:31], v[30:31], v[0:1] op_sel_hi:[1,0]
	v_pk_mul_f32 v[28:29], v[28:29], v[0:1] op_sel_hi:[1,0]
	v_pk_mul_f32 v[26:27], v[26:27], v[0:1] op_sel_hi:[1,0]
	v_pk_mul_f32 v[24:25], v[24:25], v[0:1] op_sel_hi:[1,0]
	v_pk_mul_f32 v[22:23], v[22:23], v[0:1] op_sel_hi:[1,0]
	v_pk_mul_f32 v[20:21], v[20:21], v[0:1] op_sel_hi:[1,0]
	v_pk_mul_f32 v[18:19], v[18:19], v[0:1] op_sel_hi:[1,0]
	v_pk_mul_f32 v[16:17], v[16:17], v[0:1] op_sel_hi:[1,0]
	s_branch .Lmla_join_b
	.Lmla_keep_b:
	v_mov_b32_e32 v226, v248
	v_mov_b32_e32 v0, 1.0
	.Lmla_join_b:
	v_sub_f32_e32 v248, v96, v226
	v_exp_f32_e32 v96, v248
	v_sub_f32_e32 v249, v97, v226
	v_exp_f32_e32 v97, v249
	v_sub_f32_e32 v248, v98, v226
	v_exp_f32_e32 v98, v248
	v_sub_f32_e32 v249, v99, v226
	v_exp_f32_e32 v99, v249
	v_sub_f32_e32 v248, v100, v226
	v_exp_f32_e32 v100, v248
	v_sub_f32_e32 v249, v101, v226
	v_exp_f32_e32 v101, v249
	v_sub_f32_e32 v248, v102, v226
	v_exp_f32_e32 v102, v248
	v_sub_f32_e32 v249, v103, v226
	v_exp_f32_e32 v103, v249
	s_nop 0
	v_cvt_pk_bf16_f32 v8, v96, v97
	v_cvt_pk_bf16_f32 v9, v98, v99
	v_cvt_pk_bf16_f32 v10, v100, v101
	v_cvt_pk_bf16_f32 v11, v102, v103
	v_sub_f32_e32 v248, v104, v226
	v_exp_f32_e32 v104, v248
	v_mfma_f32_32x32x16_bf16 v[64:79], v[232:235], v[8:11], v[64:79]
	ds_read_b64 v[232:233], v224 offset:13056
	ds_read_b64 v[234:235], v224 offset:13072
	v_sub_f32_e32 v249, v105, v226
	v_exp_f32_e32 v105, v249
	v_mfma_f32_32x32x16_bf16 v[48:63], v[236:239], v[8:11], v[48:63]
	ds_read_b64 v[236:237], v224 offset:32
	ds_read_b64 v[238:239], v224 offset:48
	v_sub_f32_e32 v248, v106, v226
	v_exp_f32_e32 v106, v248
	v_sub_f32_e32 v249, v107, v226
	v_exp_f32_e32 v107, v249
	v_mfma_f32_32x32x16_bf16 v[32:47], v[240:243], v[8:11], v[32:47]
	ds_read_b64 v[240:241], v224 offset:4384
	ds_read_b64 v[242:243], v224 offset:4400
	v_sub_f32_e32 v248, v108, v226
	v_exp_f32_e32 v108, v248
	v_sub_f32_e32 v249, v109, v226
	v_exp_f32_e32 v109, v249
	s_waitcnt lgkmcnt(4)
	v_mfma_f32_32x32x16_bf16 v[16:31], v[232:235], v[8:11], v[16:31]
	ds_read_b64 v[232:233], v224 offset:8736
	ds_read_b64 v[234:235], v224 offset:8752
	v_sub_f32_e32 v248, v110, v226
	v_exp_f32_e32 v110, v248
	v_sub_f32_e32 v249, v111, v226
	v_exp_f32_e32 v111, v249
	s_nop 0
	v_cvt_pk_bf16_f32 v4, v104, v105
	v_cvt_pk_bf16_f32 v5, v106, v107
	v_cvt_pk_bf16_f32 v6, v108, v109
	v_cvt_pk_bf16_f32 v7, v110, v111
	s_nop 1
	s_waitcnt lgkmcnt(4)
	v_mfma_f32_32x32x16_bf16 v[64:79], v[236:239], v[4:7], v[64:79]
	ds_read_b64 v[236:237], v224 offset:13088
	ds_read_b64 v[238:239], v224 offset:13104
	v_sub_f32_e32 v248, v80, v226
	v_exp_f32_e32 v80, v248
	v_sub_f32_e32 v249, v81, v226
	v_exp_f32_e32 v81, v249
	s_waitcnt lgkmcnt(4)
	v_mfma_f32_32x32x16_bf16 v[48:63], v[240:243], v[4:7], v[48:63]
	ds_read_b64 v[240:241], v224 offset:64
	ds_read_b64 v[242:243], v224 offset:80
	v_sub_f32_e32 v248, v82, v226
	v_exp_f32_e32 v82, v248
	v_sub_f32_e32 v249, v83, v226
	v_exp_f32_e32 v83, v249
	s_waitcnt lgkmcnt(4)
	v_mfma_f32_32x32x16_bf16 v[32:47], v[232:235], v[4:7], v[32:47]
	ds_read_b64 v[232:233], v224 offset:4416
	ds_read_b64 v[234:235], v224 offset:4432
	v_sub_f32_e32 v248, v84, v226
	v_exp_f32_e32 v84, v248
	v_sub_f32_e32 v249, v85, v226
	v_exp_f32_e32 v85, v249
	s_waitcnt lgkmcnt(4)
	v_mfma_f32_32x32x16_bf16 v[16:31], v[236:239], v[4:7], v[16:31]
	ds_read_b64 v[236:237], v224 offset:8768
	ds_read_b64 v[238:239], v224 offset:8784
	v_sub_f32_e32 v248, v86, v226
	v_exp_f32_e32 v86, v248
	v_sub_f32_e32 v249, v87, v226
	v_exp_f32_e32 v87, v249
	s_nop 0
	v_cvt_pk_bf16_f32 v12, v80, v81
	v_cvt_pk_bf16_f32 v13, v82, v83
	v_cvt_pk_bf16_f32 v14, v84, v85
	v_cvt_pk_bf16_f32 v15, v86, v87
	s_nop 1
	s_waitcnt lgkmcnt(4)
	v_mfma_f32_32x32x16_bf16 v[64:79], v[240:243], v[12:15], v[64:79]
	ds_read_b64 v[240:241], v224 offset:13120
	ds_read_b64 v[242:243], v224 offset:13136
	v_sub_f32_e32 v248, v88, v226
	v_exp_f32_e32 v88, v248
	v_sub_f32_e32 v249, v89, v226
	v_exp_f32_e32 v89, v249
	s_waitcnt lgkmcnt(4)
	v_mfma_f32_32x32x16_bf16 v[48:63], v[232:235], v[12:15], v[48:63]
	ds_read_b64 v[232:233], v224 offset:96
	ds_read_b64 v[234:235], v224 offset:112
	v_sub_f32_e32 v248, v90, v226
	v_exp_f32_e32 v90, v248
	v_sub_f32_e32 v249, v91, v226
	v_exp_f32_e32 v91, v249
	s_waitcnt lgkmcnt(4)
	v_mfma_f32_32x32x16_bf16 v[32:47], v[236:239], v[12:15], v[32:47]
	ds_read_b64 v[236:237], v224 offset:4448
	ds_read_b64 v[238:239], v224 offset:4464
	v_sub_f32_e32 v248, v92, v226
	v_exp_f32_e32 v92, v248
	v_sub_f32_e32 v249, v93, v226
	v_exp_f32_e32 v93, v249
	s_waitcnt lgkmcnt(4)
	v_mfma_f32_32x32x16_bf16 v[16:31], v[240:243], v[12:15], v[16:31]
	ds_read_b64 v[240:241], v224 offset:8800
	ds_read_b64 v[242:243], v224 offset:8816
	v_sub_f32_e32 v248, v94, v226
	v_exp_f32_e32 v94, v248
	v_sub_f32_e32 v249, v95, v226
	v_exp_f32_e32 v95, v249
	s_nop 0
	v_cvt_pk_bf16_f32 v8, v88, v89
	v_cvt_pk_bf16_f32 v9, v90, v91
	v_cvt_pk_bf16_f32 v10, v92, v93
	v_cvt_pk_bf16_f32 v11, v94, v95
	s_nop 1
	s_waitcnt lgkmcnt(4)
	v_mfma_f32_32x32x16_bf16 v[64:79], v[232:235], v[8:11], v[64:79]
	ds_read_b64 v[232:233], v224 offset:13152
	ds_read_b64 v[234:235], v224 offset:13168
	v_add_f32_e32 v3, v80, v96
	v_add_f32_e32 v248, v81, v97
	v_add_f32_e32 v3, v248, v3
	v_add_f32_e32 v249, v82, v98
	v_add_f32_e32 v3, v249, v3
	v_add_f32_e32 v248, v83, v99
	v_add_f32_e32 v3, v248, v3
	v_add_f32_e32 v249, v84, v100
	s_waitcnt lgkmcnt(4)
	v_mfma_f32_32x32x16_bf16 v[48:63], v[236:239], v[8:11], v[48:63]
	v_add_f32_e32 v3, v249, v3
	v_add_f32_e32 v248, v85, v101
	v_add_f32_e32 v3, v248, v3
	v_add_f32_e32 v249, v86, v102
	v_add_f32_e32 v3, v249, v3
	v_add_f32_e32 v248, v87, v103
	v_add_f32_e32 v3, v248, v3
	v_add_f32_e32 v249, v88, v104
	s_waitcnt lgkmcnt(2)
	v_mfma_f32_32x32x16_bf16 v[32:47], v[240:243], v[8:11], v[32:47]
	v_add_f32_e32 v3, v249, v3
	v_add_f32_e32 v248, v89, v105
	v_add_f32_e32 v3, v248, v3
	v_add_f32_e32 v249, v90, v106
	v_add_f32_e32 v3, v249, v3
	v_add_f32_e32 v248, v91, v107
	v_add_f32_e32 v3, v248, v3
	v_add_f32_e32 v249, v92, v108
	s_waitcnt lgkmcnt(0)
	v_mfma_f32_32x32x16_bf16 v[16:31], v[232:235], v[8:11], v[16:31]
	v_add_f32_e32 v3, v249, v3
	v_add_f32_e32 v248, v93, v109
	v_add_f32_e32 v3, v248, v3
	v_add_f32_e32 v249, v94, v110
	v_add_f32_e32 v3, v249, v3
	v_add_f32_e32 v248, v95, v111
	v_add_f32_e32 v3, v248, v3
	v_fmac_f32_e32 v3, v221, v0
	v_mov_b32_e32 v221, v3
	s_branch .LBB0_1557

; __device__ __forceinline__ void ln_phase(const Params& P, const float* g, const float* b, bf16_t* xb) {
;     ...
;         float* y = P.out + O_Y + (size_t)row * 2048;
;         float4 v[8]; float s = 0.f;
; #pragma unroll
;         for (int i = 0; i < 8; ++i) { v[i] = *(const float4*)(y + (i * 64 + lane) * 4); s += (v[i].x + v[i].y) + (v[i].z + v[i].w); }
;         s = halfsum32(s); s += __shfl_xor(s, 32);
;         const float mu = s * (1.0f / 2048.0f); float q = 0.f;
;     ...
;         for (int i = 0; i < 8; ++i) { const int c = (i * 64 + lane) * 4; const float4 gg = *(const float4*)(g + c), bb = *(const float4*)(b + c);
.LBB0_2651:
	global_load_dwordx4 v[0:3], v[26:27], off offset:2048
	global_load_dwordx4 v[28:31], v[26:27], off offset:1024
	global_load_dwordx4 v[32:35], v[26:27], off offset:-1024
	global_load_dwordx4 v[36:39], v[26:27], off offset:-2048
	global_load_dwordx4 v[40:43], v[26:27], off offset:-4096
	global_load_dwordx4 v[44:47], v[26:27], off offset:-3072
	global_load_dwordx4 v[66:69], v[26:27], off
	global_load_dwordx4 v[70:73], v[26:27], off offset:3072
	s_waitcnt vmcnt(7)
	v_mov_b32_e32 v48, v1
	s_waitcnt vmcnt(6)
	v_mov_b32_e32 v52, v28
	v_mov_b32_e32 v53, v30
	v_mov_b32_e32 v54, v29
	v_mov_b32_e32 v55, v31
	s_waitcnt vmcnt(5)
	v_mov_b32_e32 v56, v33
	v_mov_b32_e32 v74, v35
	s_waitcnt vmcnt(4)
	v_mov_b32_e32 v76, v36
	v_mov_b32_e32 v77, v38
	v_mov_b32_e32 v78, v37
	v_mov_b32_e32 v79, v39
	s_waitcnt vmcnt(3)
	v_mov_b32_e32 v80, v40
	s_waitcnt vmcnt(2)
	v_mov_b32_e32 v81, v44
	v_mov_b32_e32 v82, v41
	v_mov_b32_e32 v83, v45
	v_mov_b32_e32 v84, v42
	v_mov_b32_e32 v85, v46
	v_mov_b32_e32 v86, v43
	v_mov_b32_e32 v87, v47
	v_pk_add_f32 v[52:53], v[52:53], v[54:55]
	v_pk_add_f32 v[54:55], v[32:33], v[56:57]
	v_pk_add_f32 v[56:57], v[34:35], v[74:75]
	v_pk_add_f32 v[74:75], v[76:77], v[78:79]
	v_pk_add_f32 v[76:77], v[80:81], v[82:83]
	v_pk_add_f32 v[78:79], v[84:85], v[86:87]
	s_waitcnt vmcnt(1)
	v_mov_b32_e32 v49, v66
	v_pk_add_f32 v[76:77], v[76:77], v[78:79]
	v_pk_add_f32 v[88:89], v[0:1], v[48:49]
	v_pk_add_f32 v[74:75], v[74:75], v[74:75] op_sel:[0,1] op_sel_hi:[1,0]
	v_add_f32_e32 v48, 0, v76
	v_mov_b32_e32 v55, v68
	v_mov_b32_e32 v57, v69
	v_mov_b32_e32 v75, v67
	v_add_f32_e32 v48, v48, v77
	v_pk_add_f32 v[54:55], v[54:55], v[56:57]
	v_pk_add_f32 v[48:49], v[48:49], v[74:75]
	v_mov_b32_e32 v50, v3
	v_pk_add_f32 v[48:49], v[48:49], v[54:55]
	v_pk_add_f32 v[50:51], v[2:3], v[50:51]
	v_pk_add_f32 v[52:53], v[52:53], v[52:53] op_sel:[0,1] op_sel_hi:[1,0]
	v_pk_add_f32 v[48:49], v[48:49], v[48:49] op_sel:[0,1] op_sel_hi:[1,0]
	s_waitcnt vmcnt(0)
	v_mov_b32_e32 v89, v72
	v_mov_b32_e32 v51, v73
	v_mov_b32_e32 v53, v71
	v_mov_b32_e32 v49, v70
	v_pk_add_f32 v[50:51], v[88:89], v[50:51]
	v_pk_add_f32 v[48:49], v[48:49], v[52:53]
	s_nop 1
	v_mov_b64_e32 v[74:75], v[128:129]
	v_mov_b64_e32 v[76:77], v[130:131]
	s_nop 1
	v_mov_b64_e32 v[78:79], v[132:133]
	v_mov_b64_e32 v[80:81], v[134:135]
	v_pk_add_f32 v[48:49], v[48:49], v[50:51]
	s_nop 0
	v_add_f32_e32 v48, v48, v49
	s_nop 1
	v_add_f32_dpp v48, v48, v48 quad_perm:[1,0,3,2] row_mask:0xf bank_mask:0xf
	s_nop 1
	v_add_f32_dpp v48, v48, v48 quad_perm:[2,3,0,1] row_mask:0xf bank_mask:0xf
	s_nop 1
	v_add_f32_dpp v48, v48, v48 row_half_mirror row_mask:0xf bank_mask:0xf
	s_nop 1
	v_add_f32_dpp v48, v48, v48 row_mirror row_mask:0xf bank_mask:0xf
	ds_bpermute_b32 v49, v62, v48
	s_waitcnt lgkmcnt(0)
	v_add_f32_e32 v48, v48, v49
	ds_bpermute_b32 v49, v63, v48
	s_waitcnt lgkmcnt(0)
; __device__ __forceinline__ unsigned pk_bf16(float lo, float hi) { unsigned r; asm("v_cvt_pk_bf16_f32 %0, %1, %2" : "=v"(r) : "v"(lo), "v"(hi)); return r; }
; __device__ __forceinline__ void ln_phase(const Params& P, const float* g, const float* b, bf16_t* xb) {
;     ...
;         const float mu = s * (1.0f / 2048.0f); float q = 0.f;
; #pragma unroll
;         for (int i = 0; i < 8; ++i) { v[i].x -= mu; v[i].y -= mu; v[i].z -= mu; v[i].w -= mu; q += (v[i].x * v[i].x + v[i].y * v[i].y) + (v[i].z * v[i].z + v[i].w * v[i].w); }
;         q = halfsum32(q); q += __shfl_xor(q, 32);
;         const float rstd = rsqrtf(q * (1.0f / 2048.0f) + 1e-5f);
; #pragma unroll
;         for (int i = 0; i < 8; ++i) { const int c = (i * 64 + lane) * 4; const float4 gg = *(const float4*)(g + c), bb = *(const float4*)(b + c);
;             float4 o; o.x = v[i].x * rstd * gg.x + bb.x; o.y = v[i].y * rstd * gg.y + bb.y; o.z = v[i].z * rstd * gg.z + bb.z; o.w = v[i].w * rstd * gg.w + bb.w;
;             *(float4*)(y + c) = o;
;             if (xb) { uint2 w; w.x = pk_bf16(o.x, o.y); w.y = pk_bf16(o.z, o.w); *(uint2*)(xb + (size_t)row * 2048 + c) = w; } }
	v_add_f32_e32 v48, v48, v49
	v_mul_f32_e32 v48, 0x3a000000, v48
	v_pk_add_f32 v[82:83], v[40:41], v[48:49] op_sel_hi:[1,0] neg_lo:[0,1] neg_hi:[0,1]
	v_pk_add_f32 v[84:85], v[42:43], v[48:49] op_sel_hi:[1,0] neg_lo:[0,1] neg_hi:[0,1]
	v_pk_add_f32 v[54:55], v[44:45], v[48:49] op_sel_hi:[1,0] neg_lo:[0,1] neg_hi:[0,1]
	v_pk_add_f32 v[56:57], v[46:47], v[48:49] op_sel_hi:[1,0] neg_lo:[0,1] neg_hi:[0,1]
	v_pk_add_f32 v[50:51], v[36:37], v[48:49] op_sel_hi:[1,0] neg_lo:[0,1] neg_hi:[0,1]
	v_pk_add_f32 v[52:53], v[38:39], v[48:49] op_sel_hi:[1,0] neg_lo:[0,1] neg_hi:[0,1]
	v_pk_add_f32 v[46:47], v[34:35], v[48:49] op_sel_hi:[1,0] neg_lo:[0,1] neg_hi:[0,1]
	v_pk_add_f32 v[40:41], v[66:67], v[48:49] op_sel_hi:[1,0] neg_lo:[0,1] neg_hi:[0,1]
	v_pk_add_f32 v[34:35], v[2:3], v[48:49] op_sel_hi:[1,0] neg_lo:[0,1] neg_hi:[0,1]
	v_mov_b32_e32 v2, v83
	v_mov_b32_e32 v3, v55
	v_mov_b32_e32 v66, v85
	v_mov_b32_e32 v67, v57
	v_pk_add_f32 v[44:45], v[32:33], v[48:49] op_sel_hi:[1,0] neg_lo:[0,1] neg_hi:[0,1]
	v_pk_add_f32 v[42:43], v[68:69], v[48:49] op_sel_hi:[1,0] neg_lo:[0,1] neg_hi:[0,1]
	v_pk_add_f32 v[36:37], v[28:29], v[48:49] op_sel_hi:[1,0] neg_lo:[0,1] neg_hi:[0,1]
	v_pk_add_f32 v[38:39], v[30:31], v[48:49] op_sel_hi:[1,0] neg_lo:[0,1] neg_hi:[0,1]
	v_pk_add_f32 v[32:33], v[0:1], v[48:49] op_sel_hi:[1,0] neg_lo:[0,1] neg_hi:[0,1]
	v_pk_add_f32 v[28:29], v[70:71], v[48:49] op_sel_hi:[1,0] neg_lo:[0,1] neg_hi:[0,1]
	v_pk_add_f32 v[30:31], v[72:73], v[48:49] op_sel_hi:[1,0] neg_lo:[0,1] neg_hi:[0,1]
	v_mov_b32_e32 v0, v82
	v_mov_b32_e32 v1, v54
	v_mov_b32_e32 v48, v84
	v_mov_b32_e32 v49, v56
	v_mov_b32_e32 v70, v51
	v_mov_b32_e32 v71, v53
	v_pk_mul_f32 v[2:3], v[2:3], v[2:3]
	v_pk_mul_f32 v[66:67], v[66:67], v[66:67]
	v_mov_b32_e32 v68, v50
	v_mov_b32_e32 v69, v52
	v_pk_mul_f32 v[70:71], v[70:71], v[70:71]
	v_pk_fma_f32 v[0:1], v[0:1], v[0:1], v[2:3]
	v_pk_fma_f32 v[2:3], v[48:49], v[48:49], v[66:67]
	v_mul_f32_e32 v72, v44, v44
	v_mul_f32_e32 v86, v46, v46
	v_pk_fma_f32 v[48:49], v[68:69], v[68:69], v[70:71]
	v_pk_add_f32 v[0:1], v[0:1], v[2:3]
	v_pk_mul_f32 v[88:89], v[40:41], v[40:41]
	v_pk_mul_f32 v[90:91], v[42:43], v[42:43]
	v_pk_fma_f32 v[72:73], v[44:45], v[44:45], v[72:73] op_sel_hi:[1,1,0]
	v_pk_fma_f32 v[86:87], v[46:47], v[46:47], v[86:87] op_sel_hi:[1,1,0]
	v_pk_add_f32 v[2:3], v[48:49], v[48:49] op_sel_hi:[0,1]
	v_pk_add_f32 v[0:1], v[0:1], v[0:1] op_sel_hi:[0,1]
	v_mov_b32_e32 v94, v37
	v_mov_b32_e32 v95, v39
	v_mov_b32_e32 v72, v88
	v_mov_b32_e32 v86, v89
	v_mov_b32_e32 v2, v90
	v_mov_b32_e32 v0, v91
	v_mov_b32_e32 v92, v36
	v_mov_b32_e32 v93, v38
	v_pk_mul_f32 v[94:95], v[94:95], v[94:95]
	v_pk_add_f32 v[48:49], v[72:73], v[86:87]
	v_pk_add_f32 v[0:1], v[2:3], v[0:1]
	v_mul_f32_e32 v96, v32, v32
	v_mul_f32_e32 v98, v34, v34
	v_pk_fma_f32 v[66:67], v[92:93], v[92:93], v[94:95]
	v_pk_add_f32 v[0:1], v[48:49], v[0:1]
	v_pk_mul_f32 v[100:101], v[28:29], v[28:29]
	v_pk_mul_f32 v[102:103], v[30:31], v[30:31]
	v_pk_fma_f32 v[96:97], v[32:33], v[32:33], v[96:97] op_sel_hi:[1,1,0]
	v_pk_fma_f32 v[98:99], v[34:35], v[34:35], v[98:99] op_sel_hi:[1,1,0]
	v_pk_add_f32 v[66:67], v[66:67], v[66:67] op_sel_hi:[0,1]
	v_pk_add_f32 v[0:1], v[0:1], v[0:1] op_sel_hi:[0,1]
	v_mov_b32_e32 v96, v100
	v_mov_b32_e32 v98, v101
	v_mov_b32_e32 v66, v102
	v_mov_b32_e32 v0, v103
	v_pk_add_f32 v[68:69], v[96:97], v[98:99]
	v_pk_add_f32 v[0:1], v[66:67], v[0:1]
	s_nop 0
	v_pk_add_f32 v[0:1], v[68:69], v[0:1]
	s_nop 0
	v_add_f32_e32 v0, v0, v1
	s_nop 1
	v_add_f32_dpp v0, v0, v0 quad_perm:[1,0,3,2] row_mask:0xf bank_mask:0xf
	s_nop 1
	v_add_f32_dpp v0, v0, v0 quad_perm:[2,3,0,1] row_mask:0xf bank_mask:0xf
	s_nop 1
	v_add_f32_dpp v0, v0, v0 row_half_mirror row_mask:0xf bank_mask:0xf
	s_nop 1
	v_add_f32_dpp v0, v0, v0 row_mirror row_mask:0xf bank_mask:0xf
	ds_bpermute_b32 v1, v62, v0
	s_waitcnt lgkmcnt(0)
	v_add_f32_e32 v0, v0, v1
	ds_bpermute_b32 v1, v63, v0
	s_waitcnt lgkmcnt(0)
	v_add_f32_e32 v0, v0, v1
	v_fmamk_f32 v0, v0, 0x3a000000, v64
	v_mul_f32_e32 v1, 0x4b800000, v0
	v_cmp_gt_f32_e32 vcc, s1, v0
	s_nop 1
	v_cndmask_b32_e32 v0, v0, v1, vcc
	v_rsq_f32_e32 v0, v0
	v_cndmask_b32_e64 v1, 0, 1, s[52:53]
	v_cmp_ne_u32_e64 s[6:7], 1, v1
	v_mul_f32_e32 v1, 0x45800000, v0
	v_cndmask_b32_e32 v48, v0, v1, vcc
	v_pk_mul_f32 v[0:1], v[82:83], v[48:49] op_sel_hi:[1,0]
	v_pk_mul_f32 v[2:3], v[84:85], v[48:49] op_sel_hi:[1,0]
	v_pk_fma_f32 v[0:1], v[74:75], v[0:1], v[78:79]
	v_pk_fma_f32 v[2:3], v[76:77], v[2:3], v[80:81]
	s_andn2_b64 vcc, exec, s[52:53]
	global_store_dwordx4 v[26:27], v[0:3], off offset:-4096
	s_cbranch_vccnz .LBB0_2653
	s_nop 0
	v_cvt_pk_bf16_f32 v0, v0, v1
	v_cvt_pk_bf16_f32 v1, v2, v3
	global_store_dwordx2 v[24:25], v[0:1], off offset:-3588

.LBB0_2723:
	v_add_u32_e32 v182, v148, v146
	ds_read_b128 v[166:169], v147
	ds_read_b128 v[170:173], v147 offset:4096
	ds_read_b128 v[174:177], v147 offset:8192
	ds_read_b128 v[178:181], v182 offset:24576
	ds_read_b128 v[182:185], v182 offset:28672
	s_add_i32 s17, s16, 2
	s_min_u32 s18, s7, 0xf80
	s_add_i32 s19, s7, 0x80
	s_min_u32 s19, s19, 0xf80
	s_addk_i32 s7, 0x100
	v_add_u32_e32 v240, s18, v126
	v_add_u32_e32 v241, 0x40000, v240
	v_add_u32_e32 v242, 0x80000, v240
	v_add_u32_e32 v243, 0xc0000, v240
	s_waitcnt lgkmcnt(1)
	v_mfma_f32_32x32x16_bf16 v[80:95], v[166:169], v[178:181], v[80:95]
	v_add_u32_e32 v190, v148, v152
	v_add_u32_e32 v194, v157, v146
	s_waitcnt lgkmcnt(0)
	v_mfma_f32_32x32x16_bf16 v[64:79], v[166:169], v[182:185], v[64:79]
	ds_read_b128 v[166:169], v151
	s_waitcnt vmcnt(13)
	ds_write_b128 v145, v[96:99] offset:57344
	global_load_dwordx4 v[96:99], v240, s[8:9]
	v_mfma_f32_32x32x16_bf16 v[48:63], v[170:173], v[178:181], v[48:63]
	v_mfma_f32_32x32x16_bf16 v[32:47], v[170:173], v[182:185], v[32:47]
	s_waitcnt vmcnt(13)
	ds_write_b128 v149, v[100:103] offset:8192
	global_load_dwordx4 v[100:103], v241, s[8:9]
	v_mfma_f32_32x32x16_bf16 v[0:15], v[174:177], v[182:185], v[0:15]
	v_add_u32_e32 v182, v148, v150
	v_mfma_f32_32x32x16_bf16 v[16:31], v[174:177], v[178:181], v[16:31]
	ds_read_b128 v[170:173], v182 offset:24576
	ds_read_b128 v[174:177], v151 offset:4096
	ds_read_b128 v[178:181], v155 offset:8192
	ds_read_b128 v[182:185], v182 offset:28672
	ds_read_b128 v[186:189], v190 offset:24576
	s_waitcnt vmcnt(13)
	ds_write_b128 v149, v[104:107] offset:16384
	global_load_dwordx4 v[104:107], v242, s[8:9]
	s_waitcnt lgkmcnt(5)
	v_mfma_f32_32x32x16_bf16 v[80:95], v[166:169], v[170:173], v[80:95]
	s_waitcnt lgkmcnt(2)
	v_mfma_f32_32x32x16_bf16 v[64:79], v[166:169], v[182:185], v[64:79]
	s_waitcnt vmcnt(13)
	ds_write_b128 v149, v[108:111] offset:24576
	global_load_dwordx4 v[108:111], v240, s[10:11]
	v_mfma_f32_32x32x16_bf16 v[48:63], v[174:177], v[170:173], v[48:63]
	v_mfma_f32_32x32x16_bf16 v[32:47], v[174:177], v[182:185], v[32:47]
	ds_read_b128 v[166:169], v151 offset:8192
	ds_read_b128 v[174:177], v153
	s_waitcnt vmcnt(13)
	ds_write_b128 v149, v[112:115] offset:32768
	global_load_dwordx4 v[112:115], v241, s[10:11]
	s_waitcnt lgkmcnt(2)
	v_mfma_f32_32x32x16_bf16 v[16:31], v[166:169], v[170:173], v[16:31]
	v_mfma_f32_32x32x16_bf16 v[0:15], v[166:169], v[182:185], v[0:15]
	ds_read_b128 v[166:169], v190 offset:28672
	v_add_u32_e32 v190, v148, v154
	ds_read_b128 v[170:173], v190 offset:24576
	s_waitcnt vmcnt(13)
	ds_write_b128 v149, v[116:119] offset:40960
	global_load_dwordx4 v[116:119], v242, s[10:11]
	s_waitcnt lgkmcnt(4)
	v_mfma_f32_32x32x16_bf16 v[80:95], v[174:177], v[186:189], v[80:95]
	s_waitcnt lgkmcnt(2)
	v_mfma_f32_32x32x16_bf16 v[64:79], v[174:177], v[166:169], v[64:79]
	ds_read_b128 v[174:177], v153 offset:4096
	ds_read_b128 v[182:185], v153 offset:8192
	s_waitcnt vmcnt(13)
	ds_write_b128 v149, v[120:123] offset:49152
	global_load_dwordx4 v[120:123], v243, s[10:11]
	s_waitcnt lgkmcnt(2)
	v_mfma_f32_32x32x16_bf16 v[48:63], v[174:177], v[186:189], v[48:63]
	v_mfma_f32_32x32x16_bf16 v[32:47], v[174:177], v[166:169], v[32:47]
	s_waitcnt lgkmcnt(1)
	v_mfma_f32_32x32x16_bf16 v[16:31], v[182:185], v[186:189], v[16:31]
	v_mfma_f32_32x32x16_bf16 v[0:15], v[182:185], v[166:169], v[0:15]
	ds_read_b128 v[166:169], v155
	ds_read_b128 v[174:177], v155 offset:4096
	ds_read_b128 v[182:185], v190 offset:28672
	s_waitcnt lgkmcnt(0)
	s_barrier
	v_mfma_f32_32x32x16_bf16 v[80:95], v[166:169], v[170:173], v[80:95]
	v_mfma_f32_32x32x16_bf16 v[64:79], v[166:169], v[182:185], v[64:79]
	v_mfma_f32_32x32x16_bf16 v[48:63], v[174:177], v[170:173], v[48:63]
	v_mfma_f32_32x32x16_bf16 v[32:47], v[174:177], v[182:185], v[32:47]
	ds_read_b128 v[166:169], v147 offset:57344
	ds_read_b128 v[174:177], v147 offset:61440
	ds_read_b128 v[186:189], v156 offset:8192
	ds_read_b128 v[190:193], v162
	v_mfma_f32_32x32x16_bf16 v[16:31], v[178:181], v[170:173], v[16:31]
	ds_read_b128 v[170:173], v194 offset:4096
	v_add_u32_e32 v240, s19, v126
	v_add_u32_e32 v241, 0x40000, v240
	v_add_u32_e32 v242, 0x80000, v240
	v_add_u32_e32 v243, 0xc0000, v240
	s_waitcnt vmcnt(13)
	ds_write_b128 v145, v[212:215]
	global_load_dwordx4 v[212:215], v240, s[8:9]
	v_mfma_f32_32x32x16_bf16 v[0:15], v[178:181], v[182:185], v[0:15]
	s_waitcnt lgkmcnt(2)
	v_mfma_f32_32x32x16_bf16 v[80:95], v[166:169], v[190:193], v[80:95]
	v_add_u32_e32 v182, v157, v150
	s_mov_b32 s16, s17
	s_waitcnt lgkmcnt(1)
	v_mfma_f32_32x32x16_bf16 v[64:79], v[166:169], v[170:173], v[64:79]
	s_waitcnt vmcnt(13)
	ds_write_b128 v145, v[216:219] offset:8192
	global_load_dwordx4 v[216:219], v241, s[8:9]
	v_mfma_f32_32x32x16_bf16 v[48:63], v[174:177], v[190:193], v[48:63]
	v_mfma_f32_32x32x16_bf16 v[32:47], v[174:177], v[170:173], v[32:47]
	s_waitcnt vmcnt(13)
	ds_write_b128 v145, v[220:223] offset:16384
	global_load_dwordx4 v[220:223], v242, s[8:9]
	v_mfma_f32_32x32x16_bf16 v[16:31], v[186:189], v[190:193], v[16:31]
	v_mfma_f32_32x32x16_bf16 v[0:15], v[186:189], v[170:173], v[0:15]
	ds_read_b128 v[166:169], v151 offset:57344
	ds_read_b128 v[170:173], v163
	ds_read_b128 v[174:177], v151 offset:61440
	ds_read_b128 v[178:181], v160 offset:8192
	ds_read_b128 v[182:185], v182 offset:4096
	ds_read_b128 v[186:189], v164
	s_waitcnt vmcnt(13)
	ds_write_b128 v145, v[224:227] offset:24576
	global_load_dwordx4 v[224:227], v240, s[10:11]
	s_waitcnt lgkmcnt(5)
	v_mfma_f32_32x32x16_bf16 v[80:95], v[166:169], v[170:173], v[80:95]
	s_waitcnt lgkmcnt(2)
	v_mfma_f32_32x32x16_bf16 v[64:79], v[166:169], v[182:185], v[64:79]
	s_waitcnt vmcnt(13)
; template <int MT, bool PIN, class Epi>
; __device__ __forceinline__ void gemm_phase(const Params& P, const bf16_t* __restrict__ A, const bf16_t* __restrict__ Bt, int nM, int nN, int K, const Epi epi, char* lds) {
;     ...
;         for (int kt = 0; kt < nk; kt += 2) { G_STEP(0, kt); G_STEP(1, kt + 1); }
	ds_write_b128 v145, v[228:231] offset:32768
	global_load_dwordx4 v[228:231], v241, s[10:11]
	v_mfma_f32_32x32x16_bf16 v[48:63], v[174:177], v[170:173], v[48:63]
	v_mfma_f32_32x32x16_bf16 v[32:47], v[174:177], v[182:185], v[32:47]
	ds_read_b128 v[166:169], v158 offset:8192
	ds_read_b128 v[174:177], v159 offset:8192
	s_waitcnt vmcnt(13)
	ds_write_b128 v145, v[232:235] offset:40960
	global_load_dwordx4 v[232:235], v242, s[10:11]
	s_waitcnt lgkmcnt(2)
	v_mfma_f32_32x32x16_bf16 v[16:31], v[166:169], v[170:173], v[16:31]
	v_mfma_f32_32x32x16_bf16 v[0:15], v[166:169], v[182:185], v[0:15]
	ds_read_b128 v[166:169], v153 offset:57344
	ds_read_b128 v[170:173], v153 offset:61440
	v_add_u32_e32 v182, v157, v152
	ds_read_b128 v[182:185], v182 offset:4096
	ds_read_b128 v[190:193], v165
	s_waitcnt vmcnt(13)
	ds_write_b128 v145, v[236:239] offset:49152
	global_load_dwordx4 v[236:239], v243, s[10:11]
	s_waitcnt lgkmcnt(4)
	v_mfma_f32_32x32x16_bf16 v[80:95], v[166:169], v[186:189], v[80:95]
	s_waitcnt lgkmcnt(2)
	v_mfma_f32_32x32x16_bf16 v[64:79], v[166:169], v[182:185], v[64:79]
	v_mfma_f32_32x32x16_bf16 v[48:63], v[170:173], v[186:189], v[48:63]
	v_mfma_f32_32x32x16_bf16 v[32:47], v[170:173], v[182:185], v[32:47]
	ds_read_b128 v[166:169], v155 offset:57344
	ds_read_b128 v[170:173], v155 offset:61440
	v_mfma_f32_32x32x16_bf16 v[16:31], v[174:177], v[186:189], v[16:31]
	v_mfma_f32_32x32x16_bf16 v[0:15], v[174:177], v[182:185], v[0:15]
	v_add_u32_e32 v174, v157, v154
	ds_read_b128 v[174:177], v174 offset:4096
	s_waitcnt lgkmcnt(0)
	s_barrier
	v_mfma_f32_32x32x16_bf16 v[80:95], v[166:169], v[190:193], v[80:95]
	v_mfma_f32_32x32x16_bf16 v[64:79], v[166:169], v[174:177], v[64:79]
	v_mfma_f32_32x32x16_bf16 v[48:63], v[170:173], v[190:193], v[48:63]
	v_mfma_f32_32x32x16_bf16 v[32:47], v[170:173], v[174:177], v[32:47]
	v_mfma_f32_32x32x16_bf16 v[16:31], v[178:181], v[190:193], v[16:31]
	v_mfma_f32_32x32x16_bf16 v[0:15], v[178:181], v[174:177], v[0:15]
	s_cmp_lt_u32 s16, 28
	s_cbranch_scc1 .LBB0_2723
	v_add_u32_e32 v182, v148, v146
	ds_read_b128 v[166:169], v147
	ds_read_b128 v[170:173], v147 offset:4096
	ds_read_b128 v[174:177], v147 offset:8192
	ds_read_b128 v[178:181], v182 offset:24576
	ds_read_b128 v[182:185], v182 offset:28672
	s_add_i32 s17, s16, 2
	s_min_u32 s18, s7, 0xf80
	s_add_i32 s19, s7, 0x80
	s_min_u32 s19, s19, 0xf80
	s_addk_i32 s7, 0x100
	v_add_u32_e32 v240, s18, v126
	v_add_u32_e32 v241, 0x40000, v240
	v_add_u32_e32 v242, 0x80000, v240
	v_add_u32_e32 v243, 0xc0000, v240
	s_waitcnt lgkmcnt(1)
	v_mfma_f32_32x32x16_bf16 v[80:95], v[166:169], v[178:181], v[80:95]
	v_add_u32_e32 v190, v148, v152
	v_add_u32_e32 v194, v157, v146
	s_waitcnt lgkmcnt(0)
	v_mfma_f32_32x32x16_bf16 v[64:79], v[166:169], v[182:185], v[64:79]
	ds_read_b128 v[166:169], v151
	s_waitcnt vmcnt(13)
	ds_write_b128 v145, v[96:99] offset:57344
	global_load_dwordx4 v[96:99], v240, s[8:9]
	v_mfma_f32_32x32x16_bf16 v[48:63], v[170:173], v[178:181], v[48:63]
	v_mfma_f32_32x32x16_bf16 v[32:47], v[170:173], v[182:185], v[32:47]
	s_waitcnt vmcnt(13)
	ds_write_b128 v149, v[100:103] offset:8192
	global_load_dwordx4 v[100:103], v241, s[8:9]
	v_mfma_f32_32x32x16_bf16 v[0:15], v[174:177], v[182:185], v[0:15]
	v_add_u32_e32 v182, v148, v150
	v_mfma_f32_32x32x16_bf16 v[16:31], v[174:177], v[178:181], v[16:31]
	ds_read_b128 v[170:173], v182 offset:24576
	ds_read_b128 v[174:177], v151 offset:4096
	ds_read_b128 v[178:181], v155 offset:8192
	ds_read_b128 v[182:185], v182 offset:28672
	ds_read_b128 v[186:189], v190 offset:24576
	s_waitcnt vmcnt(13)
	ds_write_b128 v149, v[104:107] offset:16384
	global_load_dwordx4 v[104:107], v242, s[8:9]
	s_waitcnt lgkmcnt(5)
	v_mfma_f32_32x32x16_bf16 v[80:95], v[166:169], v[170:173], v[80:95]
	s_waitcnt lgkmcnt(2)
	v_mfma_f32_32x32x16_bf16 v[64:79], v[166:169], v[182:185], v[64:79]
	s_waitcnt vmcnt(13)
	ds_write_b128 v149, v[108:111] offset:24576
	global_load_dwordx4 v[108:111], v240, s[10:11]
	v_mfma_f32_32x32x16_bf16 v[48:63], v[174:177], v[170:173], v[48:63]
	v_mfma_f32_32x32x16_bf16 v[32:47], v[174:177], v[182:185], v[32:47]
	ds_read_b128 v[166:169], v151 offset:8192
	ds_read_b128 v[174:177], v153
	s_waitcnt vmcnt(13)
	ds_write_b128 v149, v[112:115] offset:32768
	global_load_dwordx4 v[112:115], v241, s[10:11]
	s_waitcnt lgkmcnt(2)
	v_mfma_f32_32x32x16_bf16 v[16:31], v[166:169], v[170:173], v[16:31]
	v_mfma_f32_32x32x16_bf16 v[0:15], v[166:169], v[182:185], v[0:15]
	ds_read_b128 v[166:169], v190 offset:28672
	v_add_u32_e32 v190, v148, v154
	ds_read_b128 v[170:173], v190 offset:24576
	s_waitcnt vmcnt(13)
	ds_write_b128 v149, v[116:119] offset:40960
	global_load_dwordx4 v[116:119], v242, s[10:11]
	s_waitcnt lgkmcnt(4)
	v_mfma_f32_32x32x16_bf16 v[80:95], v[174:177], v[186:189], v[80:95]
	s_waitcnt lgkmcnt(2)
	v_mfma_f32_32x32x16_bf16 v[64:79], v[174:177], v[166:169], v[64:79]
	ds_read_b128 v[174:177], v153 offset:4096
	ds_read_b128 v[182:185], v153 offset:8192
	s_waitcnt vmcnt(13)
	ds_write_b128 v149, v[120:123] offset:49152
	global_load_dwordx4 v[120:123], v243, s[10:11]
	s_waitcnt lgkmcnt(2)
	v_mfma_f32_32x32x16_bf16 v[48:63], v[174:177], v[186:189], v[48:63]
	v_mfma_f32_32x32x16_bf16 v[32:47], v[174:177], v[166:169], v[32:47]
	s_waitcnt lgkmcnt(1)
	v_mfma_f32_32x32x16_bf16 v[16:31], v[182:185], v[186:189], v[16:31]
	v_mfma_f32_32x32x16_bf16 v[0:15], v[182:185], v[166:169], v[0:15]
	ds_read_b128 v[166:169], v155
	ds_read_b128 v[174:177], v155 offset:4096
	ds_read_b128 v[182:185], v190 offset:28672
	s_waitcnt lgkmcnt(0)
	s_barrier
	v_mfma_f32_32x32x16_bf16 v[80:95], v[166:169], v[170:173], v[80:95]
	v_mfma_f32_32x32x16_bf16 v[64:79], v[166:169], v[182:185], v[64:79]
	v_mfma_f32_32x32x16_bf16 v[48:63], v[174:177], v[170:173], v[48:63]
	v_mfma_f32_32x32x16_bf16 v[32:47], v[174:177], v[182:185], v[32:47]
	ds_read_b128 v[166:169], v147 offset:57344
	ds_read_b128 v[174:177], v147 offset:61440
	ds_read_b128 v[186:189], v156 offset:8192
	ds_read_b128 v[190:193], v162
	v_mfma_f32_32x32x16_bf16 v[16:31], v[178:181], v[170:173], v[16:31]
	ds_read_b128 v[170:173], v194 offset:4096
	v_add_u32_e32 v240, s19, v126
	v_add_u32_e32 v241, 0x40000, v240
	v_add_u32_e32 v242, 0x80000, v240
	v_add_u32_e32 v243, 0xc0000, v240
	s_waitcnt vmcnt(13)
	ds_write_b128 v145, v[212:215]
	v_mfma_f32_32x32x16_bf16 v[0:15], v[178:181], v[182:185], v[0:15]
	s_waitcnt lgkmcnt(2)
	v_mfma_f32_32x32x16_bf16 v[80:95], v[166:169], v[190:193], v[80:95]
	v_add_u32_e32 v182, v157, v150
	s_mov_b32 s16, s17
	s_waitcnt lgkmcnt(1)
	v_mfma_f32_32x32x16_bf16 v[64:79], v[166:169], v[170:173], v[64:79]
	s_waitcnt vmcnt(12)
	ds_write_b128 v145, v[216:219] offset:8192
	v_mfma_f32_32x32x16_bf16 v[48:63], v[174:177], v[190:193], v[48:63]
	v_mfma_f32_32x32x16_bf16 v[32:47], v[174:177], v[170:173], v[32:47]
	s_waitcnt vmcnt(11)
	ds_write_b128 v145, v[220:223] offset:16384
	v_mfma_f32_32x32x16_bf16 v[16:31], v[186:189], v[190:193], v[16:31]
	v_mfma_f32_32x32x16_bf16 v[0:15], v[186:189], v[170:173], v[0:15]
	ds_read_b128 v[166:169], v151 offset:57344
	ds_read_b128 v[170:173], v163
	ds_read_b128 v[174:177], v151 offset:61440
	ds_read_b128 v[178:181], v160 offset:8192
	ds_read_b128 v[182:185], v182 offset:4096
	ds_read_b128 v[186:189], v164
	s_waitcnt vmcnt(10)
	ds_write_b128 v145, v[224:227] offset:24576
	s_waitcnt lgkmcnt(5)
	v_mfma_f32_32x32x16_bf16 v[80:95], v[166:169], v[170:173], v[80:95]
	s_waitcnt lgkmcnt(2)
	v_mfma_f32_32x32x16_bf16 v[64:79], v[166:169], v[182:185], v[64:79]
	s_waitcnt vmcnt(9)
	ds_write_b128 v145, v[228:231] offset:32768
	v_mfma_f32_32x32x16_bf16 v[48:63], v[174:177], v[170:173], v[48:63]
	v_mfma_f32_32x32x16_bf16 v[32:47], v[174:177], v[182:185], v[32:47]
	ds_read_b128 v[166:169], v158 offset:8192
	ds_read_b128 v[174:177], v159 offset:8192
	s_waitcnt vmcnt(8)
	ds_write_b128 v145, v[232:235] offset:40960
	s_waitcnt lgkmcnt(2)
	v_mfma_f32_32x32x16_bf16 v[16:31], v[166:169], v[170:173], v[16:31]
	v_mfma_f32_32x32x16_bf16 v[0:15], v[166:169], v[182:185], v[0:15]
	ds_read_b128 v[166:169], v153 offset:57344
	ds_read_b128 v[170:173], v153 offset:61440
	v_add_u32_e32 v182, v157, v152
	ds_read_b128 v[182:185], v182 offset:4096
	ds_read_b128 v[190:193], v165
	s_waitcnt vmcnt(7)
	ds_write_b128 v145, v[236:239] offset:49152
	s_waitcnt lgkmcnt(4)
	v_mfma_f32_32x32x16_bf16 v[80:95], v[166:169], v[186:189], v[80:95]
	s_waitcnt lgkmcnt(2)
	v_mfma_f32_32x32x16_bf16 v[64:79], v[166:169], v[182:185], v[64:79]
	v_mfma_f32_32x32x16_bf16 v[48:63], v[170:173], v[186:189], v[48:63]
	v_mfma_f32_32x32x16_bf16 v[32:47], v[170:173], v[182:185], v[32:47]
	ds_read_b128 v[166:169], v155 offset:57344
	ds_read_b128 v[170:173], v155 offset:61440
	v_mfma_f32_32x32x16_bf16 v[16:31], v[174:177], v[186:189], v[16:31]
	v_mfma_f32_32x32x16_bf16 v[0:15], v[174:177], v[182:185], v[0:15]
	v_add_u32_e32 v174, v157, v154
	ds_read_b128 v[174:177], v174 offset:4096
	s_waitcnt lgkmcnt(0)
	s_barrier
	v_mfma_f32_32x32x16_bf16 v[80:95], v[166:169], v[190:193], v[80:95]
	v_mfma_f32_32x32x16_bf16 v[64:79], v[166:169], v[174:177], v[64:79]
	v_mfma_f32_32x32x16_bf16 v[48:63], v[170:173], v[190:193], v[48:63]
	v_mfma_f32_32x32x16_bf16 v[32:47], v[170:173], v[174:177], v[32:47]
	v_mfma_f32_32x32x16_bf16 v[16:31], v[178:181], v[190:193], v[16:31]
	v_mfma_f32_32x32x16_bf16 v[0:15], v[178:181], v[174:177], v[0:15]
	v_add_u32_e32 v182, v148, v146
	ds_read_b128 v[166:169], v147
	ds_read_b128 v[170:173], v147 offset:4096
	ds_read_b128 v[174:177], v147 offset:8192
	ds_read_b128 v[178:181], v182 offset:24576
	ds_read_b128 v[182:185], v182 offset:28672
	s_add_i32 s17, s16, 2
	s_min_u32 s18, s7, 0xf80
	s_add_i32 s19, s7, 0x80
	s_min_u32 s19, s19, 0xf80
	s_addk_i32 s7, 0x100
	v_add_u32_e32 v240, s18, v126
	v_add_u32_e32 v241, 0x40000, v240
	v_add_u32_e32 v242, 0x80000, v240
	v_add_u32_e32 v243, 0xc0000, v240
	s_waitcnt lgkmcnt(1)
	v_mfma_f32_32x32x16_bf16 v[80:95], v[166:169], v[178:181], v[80:95]
	v_add_u32_e32 v190, v148, v152
	v_add_u32_e32 v194, v157, v146
	s_waitcnt lgkmcnt(0)
	v_mfma_f32_32x32x16_bf16 v[64:79], v[166:169], v[182:185], v[64:79]
	ds_read_b128 v[166:169], v151
	s_waitcnt vmcnt(6)
	ds_write_b128 v145, v[96:99] offset:57344
	v_mfma_f32_32x32x16_bf16 v[48:63], v[170:173], v[178:181], v[48:63]
	v_mfma_f32_32x32x16_bf16 v[32:47], v[170:173], v[182:185], v[32:47]
	s_waitcnt vmcnt(5)
	ds_write_b128 v149, v[100:103] offset:8192
	v_mfma_f32_32x32x16_bf16 v[0:15], v[174:177], v[182:185], v[0:15]
	v_add_u32_e32 v182, v148, v150
	v_mfma_f32_32x32x16_bf16 v[16:31], v[174:177], v[178:181], v[16:31]
	ds_read_b128 v[170:173], v182 offset:24576
	ds_read_b128 v[174:177], v151 offset:4096
	ds_read_b128 v[178:181], v155 offset:8192
	ds_read_b128 v[182:185], v182 offset:28672
	ds_read_b128 v[186:189], v190 offset:24576
	s_waitcnt vmcnt(4)
	ds_write_b128 v149, v[104:107] offset:16384
	s_waitcnt lgkmcnt(5)
	v_mfma_f32_32x32x16_bf16 v[80:95], v[166:169], v[170:173], v[80:95]
	s_waitcnt lgkmcnt(2)
	v_mfma_f32_32x32x16_bf16 v[64:79], v[166:169], v[182:185], v[64:79]
	s_waitcnt vmcnt(3)
	ds_write_b128 v149, v[108:111] offset:24576
	v_mfma_f32_32x32x16_bf16 v[48:63], v[174:177], v[170:173], v[48:63]
	v_mfma_f32_32x32x16_bf16 v[32:47], v[174:177], v[182:185], v[32:47]
	ds_read_b128 v[166:169], v151 offset:8192
	ds_read_b128 v[174:177], v153
	s_waitcnt vmcnt(2)
	ds_write_b128 v149, v[112:115] offset:32768
	s_waitcnt lgkmcnt(2)
	v_mfma_f32_32x32x16_bf16 v[16:31], v[166:169], v[170:173], v[16:31]
	v_mfma_f32_32x32x16_bf16 v[0:15], v[166:169], v[182:185], v[0:15]
	ds_read_b128 v[166:169], v190 offset:28672
	v_add_u32_e32 v190, v148, v154
	ds_read_b128 v[170:173], v190 offset:24576
	s_waitcnt vmcnt(1)
	ds_write_b128 v149, v[116:119] offset:40960
	s_waitcnt lgkmcnt(4)
	v_mfma_f32_32x32x16_bf16 v[80:95], v[174:177], v[186:189], v[80:95]
	s_waitcnt lgkmcnt(2)
	v_mfma_f32_32x32x16_bf16 v[64:79], v[174:177], v[166:169], v[64:79]
	ds_read_b128 v[174:177], v153 offset:4096
	ds_read_b128 v[182:185], v153 offset:8192
	s_waitcnt vmcnt(0)
	ds_write_b128 v149, v[120:123] offset:49152
	s_waitcnt lgkmcnt(2)
	v_mfma_f32_32x32x16_bf16 v[48:63], v[174:177], v[186:189], v[48:63]
	v_mfma_f32_32x32x16_bf16 v[32:47], v[174:177], v[166:169], v[32:47]
	s_waitcnt lgkmcnt(1)
	v_mfma_f32_32x32x16_bf16 v[16:31], v[182:185], v[186:189], v[16:31]
	v_mfma_f32_32x32x16_bf16 v[0:15], v[182:185], v[166:169], v[0:15]
	ds_read_b128 v[166:169], v155
	ds_read_b128 v[174:177], v155 offset:4096
	ds_read_b128 v[182:185], v190 offset:28672
	s_waitcnt lgkmcnt(0)
	s_barrier
; __device__ __forceinline__ bf16_t f2bf(float f) { return (bf16_t)(pk_bf16(f, f) & 0xffffu); }
;     template <int MT> __device__ __forceinline__ void run(const Params& P, f32x16 (&acc)[MT][2], int rbase, int pn, int wc, int lane) const {
;         const int n = lane & 31, hh = lane >> 5; const int rb = rbase + 4 * hh;
;         bf16_t* H = (bf16_t*)(P.ws + OFF_HFF) + pn * 64 + 32 * wc + n;
; #pragma unroll
;         for (int mt = 0; mt < MT; ++mt)
; #pragma unroll
;             for (int rg = 0; rg < 16; ++rg) { const int r = ROWOF(rb, mt, rg); const float g = acc[mt][0][rg], u = acc[mt][1][rg];
;                 const float sg = g * __builtin_amdgcn_rcpf(1.0f + __builtin_amdgcn_exp2f(-1.4426950408889634f * g));
;                 H[(size_t)r * 5632] = f2bf(sg * u); }
	v_mfma_f32_32x32x16_bf16 v[80:95], v[166:169], v[170:173], v[80:95]
	v_mfma_f32_32x32x16_bf16 v[64:79], v[166:169], v[182:185], v[64:79]
	v_mfma_f32_32x32x16_bf16 v[48:63], v[174:177], v[170:173], v[48:63]
	v_mfma_f32_32x32x16_bf16 v[32:47], v[174:177], v[182:185], v[32:47]
	ds_read_b128 v[166:169], v147 offset:57344
	ds_read_b128 v[174:177], v147 offset:61440
	ds_read_b128 v[186:189], v156 offset:8192
	ds_read_b128 v[190:193], v162
	v_mfma_f32_32x32x16_bf16 v[16:31], v[178:181], v[170:173], v[16:31]
	ds_read_b128 v[170:173], v194 offset:4096
	v_add_u32_e32 v240, s19, v126
	v_add_u32_e32 v241, 0x40000, v240
	v_add_u32_e32 v242, 0x80000, v240
	v_add_u32_e32 v243, 0xc0000, v240
	v_mfma_f32_32x32x16_bf16 v[0:15], v[178:181], v[182:185], v[0:15]
	s_waitcnt lgkmcnt(1)
	v_mfma_f32_32x32x16_bf16 v[80:95], v[166:169], v[190:193], v[80:95]
	v_add_u32_e32 v182, v157, v150
	s_mov_b32 s16, s17
	s_waitcnt lgkmcnt(0)
	v_mfma_f32_32x32x16_bf16 v[64:79], v[166:169], v[170:173], v[64:79]
	v_mfma_f32_32x32x16_bf16 v[48:63], v[174:177], v[190:193], v[48:63]
	v_mfma_f32_32x32x16_bf16 v[32:47], v[174:177], v[170:173], v[32:47]
	v_mfma_f32_32x32x16_bf16 v[16:31], v[186:189], v[190:193], v[16:31]
	v_mfma_f32_32x32x16_bf16 v[0:15], v[186:189], v[170:173], v[0:15]
	ds_read_b128 v[166:169], v151 offset:57344
	ds_read_b128 v[170:173], v163
	ds_read_b128 v[174:177], v151 offset:61440
	ds_read_b128 v[178:181], v160 offset:8192
	ds_read_b128 v[182:185], v182 offset:4096
	ds_read_b128 v[186:189], v164
	s_waitcnt lgkmcnt(4)
	v_mfma_f32_32x32x16_bf16 v[80:95], v[166:169], v[170:173], v[80:95]
	s_waitcnt lgkmcnt(1)
	v_mfma_f32_32x32x16_bf16 v[64:79], v[166:169], v[182:185], v[64:79]
	v_mfma_f32_32x32x16_bf16 v[48:63], v[174:177], v[170:173], v[48:63]
	v_mfma_f32_32x32x16_bf16 v[32:47], v[174:177], v[182:185], v[32:47]
	ds_read_b128 v[166:169], v158 offset:8192
	ds_read_b128 v[174:177], v159 offset:8192
	s_waitcnt lgkmcnt(1)
	v_mfma_f32_32x32x16_bf16 v[16:31], v[166:169], v[170:173], v[16:31]
	v_mfma_f32_32x32x16_bf16 v[0:15], v[166:169], v[182:185], v[0:15]
	ds_read_b128 v[166:169], v153 offset:57344
	ds_read_b128 v[170:173], v153 offset:61440
	v_add_u32_e32 v182, v157, v152
	ds_read_b128 v[182:185], v182 offset:4096
	ds_read_b128 v[190:193], v165
	s_waitcnt lgkmcnt(3)
	v_mfma_f32_32x32x16_bf16 v[80:95], v[166:169], v[186:189], v[80:95]
	s_waitcnt lgkmcnt(1)
	v_mfma_f32_32x32x16_bf16 v[64:79], v[166:169], v[182:185], v[64:79]
	v_mfma_f32_32x32x16_bf16 v[48:63], v[170:173], v[186:189], v[48:63]
	v_mfma_f32_32x32x16_bf16 v[32:47], v[170:173], v[182:185], v[32:47]
	ds_read_b128 v[166:169], v155 offset:57344
	ds_read_b128 v[170:173], v155 offset:61440
	v_mfma_f32_32x32x16_bf16 v[16:31], v[174:177], v[186:189], v[16:31]
	v_mfma_f32_32x32x16_bf16 v[0:15], v[174:177], v[182:185], v[0:15]
	v_add_u32_e32 v174, v157, v154
	ds_read_b128 v[174:177], v174 offset:4096
	s_waitcnt lgkmcnt(0)
	s_barrier
	v_mfma_f32_32x32x16_bf16 v[80:95], v[166:169], v[190:193], v[80:95]
	v_mfma_f32_32x32x16_bf16 v[64:79], v[166:169], v[174:177], v[64:79]
	v_mfma_f32_32x32x16_bf16 v[48:63], v[170:173], v[190:193], v[48:63]
	v_mfma_f32_32x32x16_bf16 v[32:47], v[170:173], v[174:177], v[32:47]
	v_mfma_f32_32x32x16_bf16 v[16:31], v[178:181], v[190:193], v[16:31]
	v_mfma_f32_32x32x16_bf16 v[0:15], v[178:181], v[174:177], v[0:15]
	s_nop 1
	s_waitcnt vmcnt(0)
	s_nop 4
	v_mul_f32_e32 v96, 0xbfb8aa3b, v80
	v_exp_f32_e32 v96, v96
	s_waitcnt vmcnt(4)
	v_mul_f32_e32 v100, 0xbfb8aa3b, v81
	v_exp_f32_e32 v100, v100
	s_lshl_b32 s6, s6, 7
	v_add_f32_e32 v96, 1.0, v96
	v_rcp_f32_e32 v99, v96
	s_or_b32 s6, s6, s13
	s_mulk_i32 s15, 0xc0
	s_ashr_i32 s7, s6, 31
	v_mul_f32_e32 v80, v80, v99
	v_mul_f32_e32 v64, v64, v80
	v_add_f32_e32 v80, 1.0, v100
	v_rcp_f32_e32 v80, v80
	v_add_u32_e32 v98, s15, v161
	v_lshl_add_u64 v[96:97], s[6:7], 1, v[140:141]
	v_cvt_pk_bf16_f32 v64, v64, v64
	v_mul_f32_e32 v80, v81, v80
	v_mul_f32_e32 v65, v65, v80
	v_cvt_pk_bf16_f32 v80, v65, v65
	v_mul_f32_e32 v65, 0xbfb8aa3b, v82
	v_exp_f32_e32 v81, v65
	v_mad_i64_i32 v[100:101], s[6:7], v98, s14, v[96:97]
	v_mov_b64_e32 v[250:251], v[100:101]
	global_store_short v[100:101], v64, off
	s_mov_b64 s[98:99], 0x2c00
	v_lshl_add_u64 v[64:65], v[250:251], 0, s[98:99]
	global_store_short v[64:65], v80, off
	v_add_f32_e32 v64, 1.0, v81
	v_rcp_f32_e32 v64, v64
	v_mul_f32_e32 v80, 0xbfb8aa3b, v83
	v_exp_f32_e32 v80, v80
	s_mov_b64 s[98:99], 0x5800
	v_mul_f32_e32 v64, v82, v64
	v_mul_f32_e32 v64, v66, v64
	v_cvt_pk_bf16_f32 v66, v64, v64
	v_add_f32_e32 v64, 1.0, v80
	v_rcp_f32_e32 v80, v64
	v_lshl_add_u64 v[64:65], v[250:251], 0, s[98:99]
	global_store_short v[64:65], v66, off
	v_mul_f32_e32 v65, v83, v80
	v_mul_f32_e32 v65, v67, v65
	v_cvt_pk_bf16_f32 v66, v65, v65
	v_mul_f32_e32 v65, 0xbfb8aa3b, v84
	v_exp_f32_e32 v67, v65
	s_mov_b64 s[98:99], 0x8400
	v_lshl_add_u64 v[64:65], v[250:251], 0, s[98:99]
	global_store_short v[64:65], v66, off
	v_add_f32_e32 v64, 1.0, v67
	v_rcp_f32_e32 v64, v64
	v_mul_f32_e32 v66, 0xbfb8aa3b, v85
	v_exp_f32_e32 v66, v66
	s_mov_b64 s[98:99], 0x16000
	v_mul_f32_e32 v64, v84, v64
	v_mul_f32_e32 v64, v68, v64
	v_cvt_pk_bf16_f32 v67, v64, v64
	v_add_f32_e32 v64, 1.0, v66
	v_rcp_f32_e32 v66, v64
	v_lshl_add_u64 v[64:65], v[250:251], 0, s[98:99]
	global_store_short v[64:65], v67, off
	v_mul_f32_e32 v65, v85, v66
	v_mul_f32_e32 v65, v69, v65
	v_cvt_pk_bf16_f32 v66, v65, v65
	v_mul_f32_e32 v65, 0xbfb8aa3b, v86
	v_exp_f32_e32 v67, v65
	s_mov_b64 s[98:99], 0x18c00
	v_lshl_add_u64 v[64:65], v[250:251], 0, s[98:99]
	global_store_short v[64:65], v66, off
	v_add_f32_e32 v64, 1.0, v67
	v_rcp_f32_e32 v64, v64
	v_mul_f32_e32 v66, 0xbfb8aa3b, v87
; __device__ __forceinline__ bf16_t f2bf(float f) { return (bf16_t)(pk_bf16(f, f) & 0xffffu); }
;     template <int MT> __device__ __forceinline__ void run(const Params& P, f32x16 (&acc)[MT][2], int rbase, int pn, int wc, int lane) const {
;     ...
;         bf16_t* H = (bf16_t*)(P.ws + OFF_HFF) + pn * 64 + 32 * wc + n;
; #pragma unroll
;         for (int mt = 0; mt < MT; ++mt)
; #pragma unroll
;             for (int rg = 0; rg < 16; ++rg) { const int r = ROWOF(rb, mt, rg); const float g = acc[mt][0][rg], u = acc[mt][1][rg];
;                 const float sg = g * __builtin_amdgcn_rcpf(1.0f + __builtin_amdgcn_exp2f(-1.4426950408889634f * g));
;                 H[(size_t)r * 5632] = f2bf(sg * u); }
	v_exp_f32_e32 v66, v66
	s_mov_b64 s[98:99], 0x1b800
	v_mul_f32_e32 v64, v86, v64
	v_mul_f32_e32 v64, v70, v64
	v_cvt_pk_bf16_f32 v67, v64, v64
	v_add_f32_e32 v64, 1.0, v66
	v_rcp_f32_e32 v66, v64
	v_lshl_add_u64 v[64:65], v[250:251], 0, s[98:99]
	global_store_short v[64:65], v67, off
	v_mul_f32_e32 v65, v87, v66
	v_mul_f32_e32 v65, v71, v65
	v_cvt_pk_bf16_f32 v66, v65, v65
	v_mul_f32_e32 v65, 0xbfb8aa3b, v88
	v_exp_f32_e32 v67, v65
	s_mov_b64 s[98:99], 0x1e400
	v_lshl_add_u64 v[64:65], v[250:251], 0, s[98:99]
	global_store_short v[64:65], v66, off
	v_add_f32_e32 v64, 1.0, v67
	v_rcp_f32_e32 v64, v64
	v_mul_f32_e32 v66, 0xbfb8aa3b, v89
	v_exp_f32_e32 v66, v66
	s_mov_b64 s[98:99], 0x2c000
	v_mul_f32_e32 v64, v88, v64
	v_mul_f32_e32 v64, v72, v64
	v_cvt_pk_bf16_f32 v67, v64, v64
	v_add_f32_e32 v64, 1.0, v66
	v_rcp_f32_e32 v66, v64
	v_lshl_add_u64 v[64:65], v[250:251], 0, s[98:99]
	global_store_short v[64:65], v67, off
	v_mul_f32_e32 v65, v89, v66
	v_mul_f32_e32 v65, v73, v65
	v_cvt_pk_bf16_f32 v66, v65, v65
	v_mul_f32_e32 v65, 0xbfb8aa3b, v90
	v_exp_f32_e32 v67, v65
	s_mov_b64 s[98:99], 0x2ec00
	v_lshl_add_u64 v[64:65], v[250:251], 0, s[98:99]
	global_store_short v[64:65], v66, off
	v_add_f32_e32 v64, 1.0, v67
	v_rcp_f32_e32 v64, v64
	v_mul_f32_e32 v66, 0xbfb8aa3b, v91
	v_exp_f32_e32 v66, v66
	s_mov_b64 s[98:99], 0x31800
	v_mul_f32_e32 v64, v90, v64
	v_mul_f32_e32 v64, v74, v64
	v_cvt_pk_bf16_f32 v67, v64, v64
	v_add_f32_e32 v64, 1.0, v66
	v_rcp_f32_e32 v66, v64
	v_lshl_add_u64 v[64:65], v[250:251], 0, s[98:99]
	global_store_short v[64:65], v67, off
	v_mul_f32_e32 v65, v91, v66
	v_mul_f32_e32 v65, v75, v65
	v_cvt_pk_bf16_f32 v66, v65, v65
	v_mul_f32_e32 v65, 0xbfb8aa3b, v92
	v_exp_f32_e32 v67, v65
	s_mov_b64 s[98:99], 0x34400
	v_lshl_add_u64 v[64:65], v[250:251], 0, s[98:99]
	global_store_short v[64:65], v66, off
	v_add_f32_e32 v64, 1.0, v67
	v_rcp_f32_e32 v64, v64
	v_mul_f32_e32 v66, 0xbfb8aa3b, v93
	v_exp_f32_e32 v66, v66
	s_mov_b64 s[98:99], 0x42000
	v_mul_f32_e32 v64, v92, v64
	v_mul_f32_e32 v64, v76, v64
	v_cvt_pk_bf16_f32 v67, v64, v64
	v_add_f32_e32 v64, 1.0, v66
	v_rcp_f32_e32 v66, v64
	v_lshl_add_u64 v[64:65], v[250:251], 0, s[98:99]
	global_store_short v[64:65], v67, off
	v_mul_f32_e32 v65, v93, v66
	v_mul_f32_e32 v65, v77, v65
	v_cvt_pk_bf16_f32 v66, v65, v65
	v_mul_f32_e32 v65, 0xbfb8aa3b, v94
	v_exp_f32_e32 v67, v65
	s_mov_b64 s[98:99], 0x44c00
	v_lshl_add_u64 v[64:65], v[250:251], 0, s[98:99]
	global_store_short v[64:65], v66, off
	v_add_f32_e32 v64, 1.0, v67
	v_rcp_f32_e32 v64, v64
	v_mul_f32_e32 v66, 0xbfb8aa3b, v95
	v_exp_f32_e32 v66, v66
	s_mov_b64 s[98:99], 0x47800
	v_mul_f32_e32 v64, v94, v64
	v_mul_f32_e32 v64, v78, v64
	v_cvt_pk_bf16_f32 v67, v64, v64
	v_add_f32_e32 v64, 1.0, v66
	v_rcp_f32_e32 v66, v64
	v_lshl_add_u64 v[64:65], v[250:251], 0, s[98:99]
	global_store_short v[64:65], v67, off
	v_mul_f32_e32 v65, v95, v66
	v_mul_f32_e32 v65, v79, v65
	v_cvt_pk_bf16_f32 v66, v65, v65
	v_mul_f32_e32 v65, 0xbfb8aa3b, v48
	v_exp_f32_e32 v67, v65
	s_mov_b64 s[98:99], 0x4a400
	v_lshl_add_u64 v[64:65], v[250:251], 0, s[98:99]
	global_store_short v[64:65], v66, off
	v_add_f32_e32 v64, 1.0, v67
	v_rcp_f32_e32 v64, v64
	v_mul_f32_e32 v66, 0xbfb8aa3b, v49
	v_exp_f32_e32 v66, v66
	s_mov_b64 s[98:99], 0x58000
	v_mul_f32_e32 v48, v48, v64
	v_mul_f32_e32 v32, v32, v48
	v_add_f32_e32 v48, 1.0, v66
	v_rcp_f32_e32 v48, v48
	v_cvt_pk_bf16_f32 v32, v32, v32
	v_lshl_add_u64 v[64:65], v[250:251], 0, s[98:99]
	v_mul_f32_e32 v48, v49, v48
	v_mul_f32_e32 v33, v33, v48
	v_cvt_pk_bf16_f32 v48, v33, v33
	v_mul_f32_e32 v33, 0xbfb8aa3b, v50
	v_exp_f32_e32 v49, v33
	global_store_short v[64:65], v32, off
	s_mov_b64 s[98:99], 0x5ac00
	v_lshl_add_u64 v[32:33], v[250:251], 0, s[98:99]
	global_store_short v[32:33], v48, off
	v_add_f32_e32 v32, 1.0, v49
	v_rcp_f32_e32 v32, v32
	v_mul_f32_e32 v48, 0xbfb8aa3b, v51
	v_exp_f32_e32 v48, v48
	s_mov_b64 s[98:99], 0x5d800
	v_mul_f32_e32 v32, v50, v32
	v_mul_f32_e32 v32, v34, v32
	v_cvt_pk_bf16_f32 v34, v32, v32
	v_add_f32_e32 v32, 1.0, v48
	v_rcp_f32_e32 v48, v32
	v_lshl_add_u64 v[32:33], v[250:251], 0, s[98:99]
	global_store_short v[32:33], v34, off
	v_mul_f32_e32 v33, v51, v48
	v_mul_f32_e32 v33, v35, v33
	v_cvt_pk_bf16_f32 v34, v33, v33
	v_mul_f32_e32 v33, 0xbfb8aa3b, v52
	v_exp_f32_e32 v35, v33
	s_mov_b64 s[98:99], 0x60400
	v_lshl_add_u64 v[32:33], v[250:251], 0, s[98:99]
	global_store_short v[32:33], v34, off
	v_add_f32_e32 v32, 1.0, v35
	v_rcp_f32_e32 v32, v32
	v_mul_f32_e32 v34, 0xbfb8aa3b, v53
	v_exp_f32_e32 v34, v34
	s_mov_b64 s[98:99], 0x6e000
	v_mul_f32_e32 v32, v52, v32
	v_mul_f32_e32 v32, v36, v32
	v_cvt_pk_bf16_f32 v35, v32, v32
	v_add_f32_e32 v32, 1.0, v34
	v_rcp_f32_e32 v34, v32
	v_lshl_add_u64 v[32:33], v[250:251], 0, s[98:99]
	global_store_short v[32:33], v35, off
	v_mul_f32_e32 v33, v53, v34
	v_mul_f32_e32 v33, v37, v33
	v_cvt_pk_bf16_f32 v34, v33, v33
	v_mul_f32_e32 v33, 0xbfb8aa3b, v54
	v_exp_f32_e32 v35, v33
	s_mov_b64 s[98:99], 0x70c00
	v_lshl_add_u64 v[32:33], v[250:251], 0, s[98:99]
	global_store_short v[32:33], v34, off
	v_add_f32_e32 v32, 1.0, v35
	v_rcp_f32_e32 v32, v32
	v_mul_f32_e32 v34, 0xbfb8aa3b, v55
	v_exp_f32_e32 v34, v34
	s_mov_b64 s[98:99], 0x73800
	v_mul_f32_e32 v32, v54, v32
	v_mul_f32_e32 v32, v38, v32
	v_cvt_pk_bf16_f32 v35, v32, v32
	v_add_f32_e32 v32, 1.0, v34
	v_rcp_f32_e32 v34, v32
	v_lshl_add_u64 v[32:33], v[250:251], 0, s[98:99]
	global_store_short v[32:33], v35, off
	v_mul_f32_e32 v33, v55, v34
	v_mul_f32_e32 v33, v39, v33
	v_cvt_pk_bf16_f32 v34, v33, v33
	v_mul_f32_e32 v33, 0xbfb8aa3b, v56
	v_exp_f32_e32 v35, v33
	s_mov_b64 s[98:99], 0x76400
; __device__ __forceinline__ bf16_t f2bf(float f) { return (bf16_t)(pk_bf16(f, f) & 0xffffu); }
;     template <int MT> __device__ __forceinline__ void run(const Params& P, f32x16 (&acc)[MT][2], int rbase, int pn, int wc, int lane) const {
;     ...
;         bf16_t* H = (bf16_t*)(P.ws + OFF_HFF) + pn * 64 + 32 * wc + n;
; #pragma unroll
;         for (int mt = 0; mt < MT; ++mt)
; #pragma unroll
;             for (int rg = 0; rg < 16; ++rg) { const int r = ROWOF(rb, mt, rg); const float g = acc[mt][0][rg], u = acc[mt][1][rg];
;                 const float sg = g * __builtin_amdgcn_rcpf(1.0f + __builtin_amdgcn_exp2f(-1.4426950408889634f * g));
;                 H[(size_t)r * 5632] = f2bf(sg * u); }
	v_lshl_add_u64 v[32:33], v[250:251], 0, s[98:99]
	global_store_short v[32:33], v34, off
	v_add_f32_e32 v32, 1.0, v35
	v_rcp_f32_e32 v32, v32
	v_mul_f32_e32 v34, 0xbfb8aa3b, v57
	v_exp_f32_e32 v34, v34
	s_mov_b64 s[98:99], 0x84000
	v_mul_f32_e32 v32, v56, v32
	v_mul_f32_e32 v32, v40, v32
	v_cvt_pk_bf16_f32 v35, v32, v32
	v_add_f32_e32 v32, 1.0, v34
	v_rcp_f32_e32 v34, v32
	v_lshl_add_u64 v[32:33], v[250:251], 0, s[98:99]
	global_store_short v[32:33], v35, off
	v_mul_f32_e32 v33, v57, v34
	v_mul_f32_e32 v33, v41, v33
	v_cvt_pk_bf16_f32 v34, v33, v33
	v_mul_f32_e32 v33, 0xbfb8aa3b, v58
	v_exp_f32_e32 v35, v33
	s_mov_b64 s[98:99], 0x86c00
	v_lshl_add_u64 v[32:33], v[250:251], 0, s[98:99]
	global_store_short v[32:33], v34, off
	v_add_f32_e32 v32, 1.0, v35
	v_rcp_f32_e32 v32, v32
	v_mul_f32_e32 v34, 0xbfb8aa3b, v59
	v_exp_f32_e32 v34, v34
	s_mov_b64 s[98:99], 0x89800
	v_mul_f32_e32 v32, v58, v32
	v_mul_f32_e32 v32, v42, v32
	v_cvt_pk_bf16_f32 v35, v32, v32
	v_add_f32_e32 v32, 1.0, v34
	v_rcp_f32_e32 v34, v32
	v_lshl_add_u64 v[32:33], v[250:251], 0, s[98:99]
	global_store_short v[32:33], v35, off
	v_mul_f32_e32 v33, v59, v34
	v_mul_f32_e32 v33, v43, v33
	v_cvt_pk_bf16_f32 v34, v33, v33
	v_mul_f32_e32 v33, 0xbfb8aa3b, v60
	v_exp_f32_e32 v35, v33
	s_mov_b64 s[98:99], 0x8c400
	v_lshl_add_u64 v[32:33], v[250:251], 0, s[98:99]
	global_store_short v[32:33], v34, off
	v_add_f32_e32 v32, 1.0, v35
	v_rcp_f32_e32 v32, v32
	v_mul_f32_e32 v34, 0xbfb8aa3b, v61
	v_exp_f32_e32 v34, v34
	s_mov_b64 s[98:99], 0x9a000
	v_mul_f32_e32 v32, v60, v32
	v_mul_f32_e32 v32, v44, v32
	v_cvt_pk_bf16_f32 v35, v32, v32
	v_add_f32_e32 v32, 1.0, v34
	v_rcp_f32_e32 v34, v32
	v_lshl_add_u64 v[32:33], v[250:251], 0, s[98:99]
	global_store_short v[32:33], v35, off
	v_mul_f32_e32 v33, v61, v34
	v_mul_f32_e32 v33, v45, v33
	v_cvt_pk_bf16_f32 v34, v33, v33
	v_mul_f32_e32 v33, 0xbfb8aa3b, v62
	v_exp_f32_e32 v35, v33
	s_mov_b64 s[98:99], 0x9cc00
	v_lshl_add_u64 v[32:33], v[250:251], 0, s[98:99]
	global_store_short v[32:33], v34, off
	v_add_f32_e32 v32, 1.0, v35
	v_rcp_f32_e32 v32, v32
	v_mul_f32_e32 v34, 0xbfb8aa3b, v63
	v_exp_f32_e32 v34, v34
	s_mov_b64 s[98:99], 0x9f800
	v_mul_f32_e32 v32, v62, v32
	v_mul_f32_e32 v32, v46, v32
	v_cvt_pk_bf16_f32 v35, v32, v32
	v_add_f32_e32 v32, 1.0, v34
	v_rcp_f32_e32 v34, v32
	v_lshl_add_u64 v[32:33], v[250:251], 0, s[98:99]
	global_store_short v[32:33], v35, off
	v_mul_f32_e32 v33, v63, v34
	v_mul_f32_e32 v33, v47, v33
	v_cvt_pk_bf16_f32 v34, v33, v33
	v_mul_f32_e32 v33, 0xbfb8aa3b, v16
	v_exp_f32_e32 v35, v33
	s_mov_b64 s[98:99], 0xa2400
	v_lshl_add_u64 v[32:33], v[250:251], 0, s[98:99]
	global_store_short v[32:33], v34, off
	v_add_f32_e32 v32, 1.0, v35
	v_rcp_f32_e32 v32, v32
	v_mul_f32_e32 v34, 0xbfb8aa3b, v17
	v_exp_f32_e32 v34, v34
	s_mov_b64 s[98:99], 0xb0000
	v_mul_f32_e32 v16, v16, v32
	v_mul_f32_e32 v0, v0, v16
	v_add_f32_e32 v16, 1.0, v34
	v_rcp_f32_e32 v16, v16
	v_cvt_pk_bf16_f32 v0, v0, v0
	v_lshl_add_u64 v[32:33], v[250:251], 0, s[98:99]
	v_mul_f32_e32 v16, v17, v16
	v_mul_f32_e32 v1, v1, v16
	v_cvt_pk_bf16_f32 v16, v1, v1
	v_mul_f32_e32 v1, 0xbfb8aa3b, v18
	v_exp_f32_e32 v17, v1
	global_store_short v[32:33], v0, off
	s_mov_b64 s[98:99], 0xb2c00
	v_lshl_add_u64 v[0:1], v[250:251], 0, s[98:99]
	global_store_short v[0:1], v16, off
	v_add_f32_e32 v0, 1.0, v17
	v_rcp_f32_e32 v0, v0
	v_mul_f32_e32 v16, 0xbfb8aa3b, v19
	v_exp_f32_e32 v16, v16
	s_mov_b64 s[98:99], 0xb5800
	v_mul_f32_e32 v0, v18, v0
	v_mul_f32_e32 v0, v2, v0
	v_cvt_pk_bf16_f32 v2, v0, v0
	v_add_f32_e32 v0, 1.0, v16
	v_rcp_f32_e32 v16, v0
	v_lshl_add_u64 v[0:1], v[250:251], 0, s[98:99]
	global_store_short v[0:1], v2, off
	v_mul_f32_e32 v1, v19, v16
	v_mul_f32_e32 v1, v3, v1
	v_cvt_pk_bf16_f32 v2, v1, v1
	v_mul_f32_e32 v1, 0xbfb8aa3b, v20
; __device__ __forceinline__ bf16_t f2bf(float f) { return (bf16_t)(pk_bf16(f, f) & 0xffffu); }
;     template <int MT> __device__ __forceinline__ void run(const Params& P, f32x16 (&acc)[MT][2], int rbase, int pn, int wc, int lane) const {
;     ...
;         bf16_t* H = (bf16_t*)(P.ws + OFF_HFF) + pn * 64 + 32 * wc + n;
; #pragma unroll
;         for (int mt = 0; mt < MT; ++mt)
; #pragma unroll
;             for (int rg = 0; rg < 16; ++rg) { const int r = ROWOF(rb, mt, rg); const float g = acc[mt][0][rg], u = acc[mt][1][rg];
;                 const float sg = g * __builtin_amdgcn_rcpf(1.0f + __builtin_amdgcn_exp2f(-1.4426950408889634f * g));
;                 H[(size_t)r * 5632] = f2bf(sg * u); }
	v_exp_f32_e32 v3, v1
	s_mov_b64 s[98:99], 0xb8400
	v_lshl_add_u64 v[0:1], v[250:251], 0, s[98:99]
	global_store_short v[0:1], v2, off
	v_add_f32_e32 v0, 1.0, v3
	v_rcp_f32_e32 v0, v0
	v_mul_f32_e32 v2, 0xbfb8aa3b, v21
	v_exp_f32_e32 v2, v2
	s_mov_b64 s[98:99], 0xc6000
	v_mul_f32_e32 v0, v20, v0
	v_mul_f32_e32 v0, v4, v0
	v_cvt_pk_bf16_f32 v3, v0, v0
	v_add_f32_e32 v0, 1.0, v2
	v_rcp_f32_e32 v2, v0
	v_lshl_add_u64 v[0:1], v[250:251], 0, s[98:99]
	global_store_short v[0:1], v3, off
	v_mul_f32_e32 v1, v21, v2
	v_mul_f32_e32 v1, v5, v1
	v_cvt_pk_bf16_f32 v2, v1, v1
	v_mul_f32_e32 v1, 0xbfb8aa3b, v22
	v_exp_f32_e32 v3, v1
	s_mov_b64 s[98:99], 0xc8c00
	v_lshl_add_u64 v[0:1], v[250:251], 0, s[98:99]
	global_store_short v[0:1], v2, off
	v_add_f32_e32 v0, 1.0, v3
	v_rcp_f32_e32 v0, v0
	v_mul_f32_e32 v2, 0xbfb8aa3b, v23
	v_exp_f32_e32 v2, v2
	s_mov_b64 s[98:99], 0xcb800
	v_mul_f32_e32 v0, v22, v0
	v_mul_f32_e32 v0, v6, v0
	v_cvt_pk_bf16_f32 v3, v0, v0
	v_add_f32_e32 v0, 1.0, v2
	v_rcp_f32_e32 v2, v0
	v_lshl_add_u64 v[0:1], v[250:251], 0, s[98:99]
	global_store_short v[0:1], v3, off
	v_mul_f32_e32 v1, v23, v2
	v_mul_f32_e32 v1, v7, v1
	v_cvt_pk_bf16_f32 v2, v1, v1
	v_mul_f32_e32 v1, 0xbfb8aa3b, v24
	v_exp_f32_e32 v3, v1
	s_mov_b64 s[98:99], 0xce400
	v_lshl_add_u64 v[0:1], v[250:251], 0, s[98:99]
	global_store_short v[0:1], v2, off
	v_add_f32_e32 v0, 1.0, v3
	v_rcp_f32_e32 v0, v0
	v_mul_f32_e32 v2, 0xbfb8aa3b, v25
	v_exp_f32_e32 v2, v2
	s_mov_b64 s[98:99], 0xdc000
	v_mul_f32_e32 v0, v24, v0
	v_mul_f32_e32 v0, v8, v0
	v_cvt_pk_bf16_f32 v3, v0, v0
	v_add_f32_e32 v0, 1.0, v2
	v_rcp_f32_e32 v2, v0
	v_lshl_add_u64 v[0:1], v[250:251], 0, s[98:99]
	global_store_short v[0:1], v3, off
	v_mul_f32_e32 v1, v25, v2
	v_mul_f32_e32 v1, v9, v1
	v_cvt_pk_bf16_f32 v2, v1, v1
	v_mul_f32_e32 v1, 0xbfb8aa3b, v26
	v_exp_f32_e32 v3, v1
	s_mov_b64 s[98:99], 0xdec00
	v_lshl_add_u64 v[0:1], v[250:251], 0, s[98:99]
	global_store_short v[0:1], v2, off
	v_add_f32_e32 v0, 1.0, v3
	v_rcp_f32_e32 v0, v0
	v_mul_f32_e32 v2, 0xbfb8aa3b, v27
	v_exp_f32_e32 v2, v2
	s_mov_b64 s[98:99], 0xe1800
	v_mul_f32_e32 v0, v26, v0
	v_mul_f32_e32 v0, v10, v0
	v_cvt_pk_bf16_f32 v3, v0, v0
	v_add_f32_e32 v0, 1.0, v2
	v_rcp_f32_e32 v2, v0
	v_lshl_add_u64 v[0:1], v[250:251], 0, s[98:99]
	global_store_short v[0:1], v3, off
	v_mul_f32_e32 v1, v27, v2
	v_mul_f32_e32 v1, v11, v1
	v_cvt_pk_bf16_f32 v2, v1, v1
	v_mul_f32_e32 v1, 0xbfb8aa3b, v28
	v_exp_f32_e32 v3, v1
	s_mov_b64 s[98:99], 0xe4400
	v_lshl_add_u64 v[0:1], v[250:251], 0, s[98:99]
	global_store_short v[0:1], v2, off
	v_add_f32_e32 v0, 1.0, v3
	v_rcp_f32_e32 v0, v0
	v_mul_f32_e32 v2, 0xbfb8aa3b, v29
	v_exp_f32_e32 v2, v2
	s_mov_b64 s[98:99], 0xf2000
	v_mul_f32_e32 v0, v28, v0
	v_mul_f32_e32 v0, v12, v0
	v_cvt_pk_bf16_f32 v3, v0, v0
	v_add_f32_e32 v0, 1.0, v2
	v_rcp_f32_e32 v2, v0
	v_lshl_add_u64 v[0:1], v[250:251], 0, s[98:99]
	global_store_short v[0:1], v3, off
	v_mul_f32_e32 v1, v29, v2
	v_mul_f32_e32 v1, v13, v1
	v_cvt_pk_bf16_f32 v2, v1, v1
	v_mul_f32_e32 v1, 0xbfb8aa3b, v30
	v_exp_f32_e32 v3, v1
	s_mov_b64 s[98:99], 0xf4c00
	v_lshl_add_u64 v[0:1], v[250:251], 0, s[98:99]
	global_store_short v[0:1], v2, off
	v_add_f32_e32 v0, 1.0, v3
	v_rcp_f32_e32 v0, v0
	v_mul_f32_e32 v2, 0xbfb8aa3b, v31
	v_exp_f32_e32 v2, v2
	s_mov_b64 s[98:99], 0xf7800
	v_mul_f32_e32 v0, v30, v0
	v_mul_f32_e32 v0, v14, v0
	v_cvt_pk_bf16_f32 v3, v0, v0
	v_add_f32_e32 v0, 1.0, v2
	v_rcp_f32_e32 v2, v0
	v_lshl_add_u64 v[0:1], v[250:251], 0, s[98:99]
	global_store_short v[0:1], v3, off
	v_mul_f32_e32 v1, v31, v2
	s_mov_b64 s[98:99], 0xfa400
	v_mul_f32_e32 v1, v15, v1
	v_cvt_pk_bf16_f32 v2, v1, v1
	v_lshl_add_u64 v[0:1], v[250:251], 0, s[98:99]
	s_add_i32 s12, s12, 1
	s_mov_b64 s[8:9], 0
	global_store_short v[0:1], v2, off
	s_branch .LBB0_2720
